# P1 gemm256 K-loop: LDS-DMA issue spread between MFMA groups of the first K-half
# speedup vs baseline: 1.0138x; 1.0138x over previous
; #define GLDS_STAGE(st, kt_) do { \
;         _Pragma("unroll") for (int i_ = 0; i_ < FI; ++i_) { \
;             glds16(ap + (size_t)(32 * i_) * lda + (kt_) * 64, l3a + (st) + tid * 16 + i_ * 4096); \
;             glds16(bp + (size_t)(32 * i_) * ldb + (kt_) * 64, l3a + (st) + OPB + tid * 16 + i_ * 4096); } } while (0)
; #define GLDS_STAGE(st, kt_) do { \
;         _Pragma("unroll") for (int i_ = 0; i_ < 4; ++i_) { \
;             glds16(ap + (size_t)(64 * i_) * lda + (kt_) * 64, l3a + (st) + tid * 16 + i_ * 8192); \
;             glds16(bp + (size_t)(64 * i_) * ldb + (kt_) * 64, l3a + (st) + 32768 + tid * 16 + i_ * 8192); } } while (0)
; template <class Epi>
; DEV void gemm256_tile(const bf16_t* __restrict__ A, int lda, const bf16_t* __restrict__ Bt, int ldb, int K, unsigned char* lds, const Epi& epi) {
;     ...
;     for (int kt = 0; kt < nk; ++kt) {
;         const int cur = (kt & 1) * 65536;
;         asm volatile("s_waitcnt vmcnt(0)" ::: "memory");
;         __syncthreads();
;         if (kt + 1 < nk) GLDS_STAGE(cur ^ 65536, kt + 1);
; #pragma unroll
;         for (int kh = 0; kh < 2; ++kh) {
;             bf16x8 bfr[4];
;             const int ch = ((kh * 4 + fq) ^ sw) << 4;
; #pragma unroll
;             for (int i = 0; i < 4; ++i) bfr[i] = *(const bf16x8*)(lds + cur + boff + i * 2048 + ch);
; #pragma unroll
;             for (int mh = 0; mh < 2; ++mh) {
;                 bf16x8 af[4];
; #pragma unroll
;                 for (int i = 0; i < 4; ++i) af[i] = *(const bf16x8*)(lds + cur + aoff + (mh * 4 + i) * 2048 + ch);
; #pragma unroll
;                 for (int mi = 0; mi < 4; ++mi)
; #pragma unroll
;                     for (int ni = 0; ni < 4; ++ni) acc[mh * 4 + mi][ni] = __builtin_amdgcn_mfma_f32_16x16x32_bf16(bfr[ni], af[mi], acc[mh * 4 + mi][ni], 0, 0, 0);
;             }
;         }
.LBB0_174:
	s_and_b32 s22, s21, 0x10000
	s_xor_b32 s23, s22, 0x10000
	v_add_u32_e32 v250, s23, v142
	v_add_u32_e32 v251, s23, v156
	s_waitcnt vmcnt(0)
	s_barrier
	v_or_b32_e32 v200, s22, v175
	v_add_u32_e32 v201, s22, v157
	v_add_u32_e32 v196, v200, v174
	v_add_u32_e32 v202, v201, v174
	ds_read_b128 v[176:179], v196 offset:32768
	ds_read_b128 v[180:183], v196 offset:34816
	ds_read_b128 v[184:187], v202
	ds_read_b128 v[188:191], v202 offset:2048
	ds_read_b128 v[192:195], v196 offset:36864
	ds_read_b128 v[196:199], v196 offset:38912
	v_readfirstlane_b32 s40, v250
	v_readfirstlane_b32 s44, v251
	v_lshl_add_u64 v[238:239], v[144:145], 0, s[4:5]
	v_lshl_add_u64 v[240:241], v[144:145], 0, s[6:7]
	s_mov_b32 m0, s40
	v_lshl_add_u64 v[242:243], v[144:145], 0, s[8:9]
	global_load_lds_dwordx4 v[144:145], off
	s_mov_b32 m0, s44
	v_lshl_add_u64 v[244:245], v[146:147], 0, s[4:5]
	global_load_lds_dwordx4 v[146:147], off
	v_lshl_add_u64 v[246:247], v[146:147], 0, s[6:7]
	v_lshl_add_u64 v[248:249], v[146:147], 0, s[8:9]
	s_add_i32 s41, s40, 0x2000
	s_add_i32 s45, s44, 0x2000
	s_add_i32 s42, s40, 0x4000
	s_add_i32 s46, s44, 0x4000
	s_add_i32 s43, s40, 0x6000
	s_add_i32 s47, s44, 0x6000
	s_add_i32 s21, s21, 0x10000
	s_waitcnt lgkmcnt(3)
	v_mfma_f32_16x16x32_bf16 v[126:129], v[176:179], v[184:187], v[126:129]
	v_add_u32_e32 v200, v200, v155
	v_add_u32_e32 v201, v201, v155
	v_mfma_f32_16x16x32_bf16 v[122:125], v[180:183], v[184:187], v[122:125]
	s_waitcnt lgkmcnt(1)
	v_mfma_f32_16x16x32_bf16 v[118:121], v[192:195], v[184:187], v[118:121]
	s_waitcnt lgkmcnt(0)
	v_mfma_f32_16x16x32_bf16 v[114:117], v[196:199], v[184:187], v[114:117]
	v_mfma_f32_16x16x32_bf16 v[110:113], v[176:179], v[188:191], v[110:113]
	v_mfma_f32_16x16x32_bf16 v[106:109], v[180:183], v[188:191], v[106:109]
	v_mfma_f32_16x16x32_bf16 v[102:105], v[192:195], v[188:191], v[102:105]
	v_mfma_f32_16x16x32_bf16 v[98:101], v[196:199], v[188:191], v[98:101]
	ds_read_b128 v[184:187], v202 offset:4096
	ds_read_b128 v[188:191], v202 offset:6144
	s_mov_b32 m0, s41
	s_nop 0
	global_load_lds_dwordx4 v[238:239], off
	s_mov_b32 m0, s45
	s_nop 0
	global_load_lds_dwordx4 v[244:245], off
	s_waitcnt lgkmcnt(1)
	v_mfma_f32_16x16x32_bf16 v[94:97], v[176:179], v[184:187], v[94:97]
	v_mfma_f32_16x16x32_bf16 v[90:93], v[180:183], v[184:187], v[90:93]
	v_mfma_f32_16x16x32_bf16 v[86:89], v[192:195], v[184:187], v[86:89]
	v_mfma_f32_16x16x32_bf16 v[82:85], v[196:199], v[184:187], v[82:85]
	s_waitcnt lgkmcnt(0)
	v_mfma_f32_16x16x32_bf16 v[78:81], v[176:179], v[188:191], v[78:81]
	v_mfma_f32_16x16x32_bf16 v[74:77], v[180:183], v[188:191], v[74:77]
	v_mfma_f32_16x16x32_bf16 v[70:73], v[192:195], v[188:191], v[70:73]
	v_mfma_f32_16x16x32_bf16 v[66:69], v[196:199], v[188:191], v[66:69]
	ds_read_b128 v[184:187], v202 offset:8192
	ds_read_b128 v[188:191], v202 offset:10240
	s_mov_b32 m0, s42
	s_nop 0
	global_load_lds_dwordx4 v[240:241], off
	s_mov_b32 m0, s46
	s_nop 0
	global_load_lds_dwordx4 v[246:247], off
	s_waitcnt lgkmcnt(1)
	v_mfma_f32_16x16x32_bf16 v[62:65], v[176:179], v[184:187], v[62:65]
	v_mfma_f32_16x16x32_bf16 v[58:61], v[180:183], v[184:187], v[58:61]
	v_mfma_f32_16x16x32_bf16 v[54:57], v[192:195], v[184:187], v[54:57]
	v_mfma_f32_16x16x32_bf16 v[50:53], v[196:199], v[184:187], v[50:53]
	s_waitcnt lgkmcnt(0)
	v_mfma_f32_16x16x32_bf16 v[46:49], v[176:179], v[188:191], v[46:49]
	v_mfma_f32_16x16x32_bf16 v[42:45], v[180:183], v[188:191], v[42:45]
	v_mfma_f32_16x16x32_bf16 v[34:37], v[192:195], v[188:191], v[34:37]
	v_mfma_f32_16x16x32_bf16 v[30:33], v[196:199], v[188:191], v[30:33]
	ds_read_b128 v[184:187], v202 offset:12288
	ds_read_b128 v[188:191], v202 offset:14336
	s_mov_b32 m0, s43
	s_nop 0
	global_load_lds_dwordx4 v[242:243], off
	s_mov_b32 m0, s47
	s_nop 0
	global_load_lds_dwordx4 v[248:249], off
	v_lshl_add_u64 v[144:145], v[144:145], 0, s[10:11]
	v_lshl_add_u64 v[146:147], v[146:147], 0, s[10:11]
	s_waitcnt lgkmcnt(1)
	v_mfma_f32_16x16x32_bf16 v[26:29], v[176:179], v[184:187], v[26:29]
	v_mfma_f32_16x16x32_bf16 v[22:25], v[180:183], v[184:187], v[22:25]
	v_mfma_f32_16x16x32_bf16 v[18:21], v[192:195], v[184:187], v[18:21]
	v_mfma_f32_16x16x32_bf16 v[14:17], v[196:199], v[184:187], v[14:17]
	s_waitcnt lgkmcnt(0)
	v_mfma_f32_16x16x32_bf16 v[10:13], v[176:179], v[188:191], v[10:13]
	v_mfma_f32_16x16x32_bf16 v[6:9], v[180:183], v[188:191], v[6:9]
	ds_read_b128 v[176:179], v200 offset:32768
	ds_read_b128 v[180:183], v200 offset:34816
	v_mfma_f32_16x16x32_bf16 v[2:5], v[192:195], v[188:191], v[2:5]
	v_mfma_f32_16x16x32_bf16 v[38:41], v[196:199], v[188:191], v[38:41]
	ds_read_b128 v[184:187], v201
	ds_read_b128 v[188:191], v201 offset:2048
	ds_read_b128 v[192:195], v200 offset:36864
	ds_read_b128 v[196:199], v200 offset:38912
	s_waitcnt lgkmcnt(3)
	v_mfma_f32_16x16x32_bf16 v[126:129], v[176:179], v[184:187], v[126:129]
	v_mfma_f32_16x16x32_bf16 v[122:125], v[180:183], v[184:187], v[122:125]
	s_waitcnt lgkmcnt(1)
	v_mfma_f32_16x16x32_bf16 v[118:121], v[192:195], v[184:187], v[118:121]
	s_waitcnt lgkmcnt(0)
	v_mfma_f32_16x16x32_bf16 v[114:117], v[196:199], v[184:187], v[114:117]
	v_mfma_f32_16x16x32_bf16 v[110:113], v[176:179], v[188:191], v[110:113]
	v_mfma_f32_16x16x32_bf16 v[106:109], v[180:183], v[188:191], v[106:109]
	v_mfma_f32_16x16x32_bf16 v[102:105], v[192:195], v[188:191], v[102:105]
	v_mfma_f32_16x16x32_bf16 v[98:101], v[196:199], v[188:191], v[98:101]
	ds_read_b128 v[184:187], v201 offset:4096
	ds_read_b128 v[188:191], v201 offset:6144
	s_waitcnt lgkmcnt(1)
; DEV unsigned cvt_pk_bf16(float lo, float hi) { const f32x2_t v = {lo, hi}; const bf16x2_t b = __builtin_convertvector(v, bf16x2_t); return __builtin_bit_cast(unsigned, b); }
; template <class Epi>
; DEV void gemm256_tile(const bf16_t* __restrict__ A, int lda, const bf16_t* __restrict__ Bt, int ldb, int K, unsigned char* lds, const Epi& epi) {
;     ...
;         for (int kh = 0; kh < 2; ++kh) {
;             bf16x8 bfr[4];
;             const int ch = ((kh * 4 + fq) ^ sw) << 4;
; #pragma unroll
;             for (int i = 0; i < 4; ++i) bfr[i] = *(const bf16x8*)(lds + cur + boff + i * 2048 + ch);
; #pragma unroll
;             for (int mh = 0; mh < 2; ++mh) {
;                 bf16x8 af[4];
; #pragma unroll
;                 for (int i = 0; i < 4; ++i) af[i] = *(const bf16x8*)(lds + cur + aoff + (mh * 4 + i) * 2048 + ch);
; #pragma unroll
;                 for (int mi = 0; mi < 4; ++mi)
; #pragma unroll
;                     for (int ni = 0; ni < 4; ++ni) acc[mh * 4 + mi][ni] = __builtin_amdgcn_mfma_f32_16x16x32_bf16(bfr[ni], af[mi], acc[mh * 4 + mi][ni], 0, 0, 0);
;             }
;         }
;     }
;     ...
;     __syncthreads();
;     if constexpr (Epi::STAGE) {
; #pragma unroll
;         for (int mi = 0; mi < 8; ++mi)
; #pragma unroll
;             for (int ni = 0; ni < 4; ++ni) {
;                 const int row = wr * 128 + mi * 16 + fr, col = wc * 64 + ni * 16 + fq * 4;
;                 const f32x4 v = epi.xform(row, col, acc[mi][ni]);
;                 uint2 w; w.x = cvt_pk_bf16(v[0], v[1]); w.y = cvt_pk_bf16(v[2], v[3]);
;                 *(uint2*)(lds + row * 512 + ((((col >> 3) ^ (row & 31)) << 4) | (((col >> 2) & 1) << 3))) = w;
	v_mfma_f32_16x16x32_bf16 v[94:97], v[176:179], v[184:187], v[94:97]
	v_mfma_f32_16x16x32_bf16 v[90:93], v[180:183], v[184:187], v[90:93]
	v_mfma_f32_16x16x32_bf16 v[86:89], v[192:195], v[184:187], v[86:89]
	v_mfma_f32_16x16x32_bf16 v[82:85], v[196:199], v[184:187], v[82:85]
	s_waitcnt lgkmcnt(0)
	v_mfma_f32_16x16x32_bf16 v[78:81], v[176:179], v[188:191], v[78:81]
	v_mfma_f32_16x16x32_bf16 v[74:77], v[180:183], v[188:191], v[74:77]
	v_mfma_f32_16x16x32_bf16 v[70:73], v[192:195], v[188:191], v[70:73]
	v_mfma_f32_16x16x32_bf16 v[66:69], v[196:199], v[188:191], v[66:69]
	ds_read_b128 v[184:187], v201 offset:8192
	ds_read_b128 v[188:191], v201 offset:10240
	s_waitcnt lgkmcnt(1)
	v_mfma_f32_16x16x32_bf16 v[62:65], v[176:179], v[184:187], v[62:65]
	v_mfma_f32_16x16x32_bf16 v[58:61], v[180:183], v[184:187], v[58:61]
	v_mfma_f32_16x16x32_bf16 v[54:57], v[192:195], v[184:187], v[54:57]
	v_mfma_f32_16x16x32_bf16 v[50:53], v[196:199], v[184:187], v[50:53]
	s_waitcnt lgkmcnt(0)
	v_mfma_f32_16x16x32_bf16 v[46:49], v[176:179], v[188:191], v[46:49]
	v_mfma_f32_16x16x32_bf16 v[42:45], v[180:183], v[188:191], v[42:45]
	v_mfma_f32_16x16x32_bf16 v[34:37], v[192:195], v[188:191], v[34:37]
	v_mfma_f32_16x16x32_bf16 v[30:33], v[196:199], v[188:191], v[30:33]
	ds_read_b128 v[184:187], v201 offset:12288
	ds_read_b128 v[188:191], v201 offset:14336
	s_waitcnt lgkmcnt(1)
	v_mfma_f32_16x16x32_bf16 v[26:29], v[176:179], v[184:187], v[26:29]
	v_mfma_f32_16x16x32_bf16 v[22:25], v[180:183], v[184:187], v[22:25]
	v_mfma_f32_16x16x32_bf16 v[18:21], v[192:195], v[184:187], v[18:21]
	v_mfma_f32_16x16x32_bf16 v[14:17], v[196:199], v[184:187], v[14:17]
	s_waitcnt lgkmcnt(0)
	v_mfma_f32_16x16x32_bf16 v[10:13], v[176:179], v[188:191], v[10:13]
	v_mfma_f32_16x16x32_bf16 v[6:9], v[180:183], v[188:191], v[6:9]
	v_mfma_f32_16x16x32_bf16 v[2:5], v[192:195], v[188:191], v[2:5]
	v_mfma_f32_16x16x32_bf16 v[38:41], v[196:199], v[188:191], v[38:41]
	s_cmp_eq_u32 s21, 0x1f0000
	s_cbranch_scc0 .LBB0_174
	v_or_b32_e32 v156, 0x18000, v175
	v_add_u32_e32 v157, 0x10000, v157
	v_add_u32_e32 v186, v156, v174
	v_add_u32_e32 v194, v157, v174
	s_waitcnt vmcnt(0)
	s_barrier
	ds_read_b128 v[144:147], v186
	ds_read_b128 v[178:181], v186 offset:2048
	ds_read_b128 v[174:177], v194
	ds_read_b128 v[182:185], v186 offset:4096
	ds_read_b128 v[186:189], v186 offset:6144
	s_waitcnt lgkmcnt(2)
	v_mfma_f32_16x16x32_bf16 v[126:129], v[144:147], v[174:177], v[126:129]
	s_sext_i32_i16 s20, s20
	s_lshl_b32 s20, s20, 8
	s_ashr_i32 s21, s20, 31
	v_mfma_f32_16x16x32_bf16 v[122:125], v[178:181], v[174:177], v[122:125]
	s_waitcnt lgkmcnt(1)
	v_mfma_f32_16x16x32_bf16 v[118:121], v[182:185], v[174:177], v[118:121]
	s_waitcnt lgkmcnt(0)
	v_mfma_f32_16x16x32_bf16 v[114:117], v[186:189], v[174:177], v[114:117]
	ds_read_b128 v[174:177], v194 offset:2048
	s_waitcnt lgkmcnt(0)
	v_mfma_f32_16x16x32_bf16 v[110:113], v[144:147], v[174:177], v[110:113]
	v_mfma_f32_16x16x32_bf16 v[106:109], v[178:181], v[174:177], v[106:109]
	v_mfma_f32_16x16x32_bf16 v[102:105], v[182:185], v[174:177], v[102:105]
	v_mfma_f32_16x16x32_bf16 v[98:101], v[186:189], v[174:177], v[98:101]
	ds_read_b128 v[174:177], v194 offset:4096
	s_waitcnt lgkmcnt(0)
	v_mfma_f32_16x16x32_bf16 v[94:97], v[144:147], v[174:177], v[94:97]
	v_mfma_f32_16x16x32_bf16 v[90:93], v[178:181], v[174:177], v[90:93]
	v_mfma_f32_16x16x32_bf16 v[86:89], v[182:185], v[174:177], v[86:89]
	v_mfma_f32_16x16x32_bf16 v[82:85], v[186:189], v[174:177], v[82:85]
	ds_read_b128 v[174:177], v194 offset:6144
	s_waitcnt lgkmcnt(0)
	v_mfma_f32_16x16x32_bf16 v[78:81], v[144:147], v[174:177], v[78:81]
	v_mfma_f32_16x16x32_bf16 v[74:77], v[178:181], v[174:177], v[74:77]
	v_mfma_f32_16x16x32_bf16 v[70:73], v[182:185], v[174:177], v[70:73]
	v_mfma_f32_16x16x32_bf16 v[66:69], v[186:189], v[174:177], v[66:69]
	ds_read_b128 v[174:177], v194 offset:8192
	ds_read_b128 v[190:193], v194 offset:10240
	s_waitcnt lgkmcnt(1)
	v_mfma_f32_16x16x32_bf16 v[62:65], v[144:147], v[174:177], v[62:65]
	v_mfma_f32_16x16x32_bf16 v[58:61], v[178:181], v[174:177], v[58:61]
	v_mfma_f32_16x16x32_bf16 v[54:57], v[182:185], v[174:177], v[54:57]
	v_mfma_f32_16x16x32_bf16 v[50:53], v[186:189], v[174:177], v[50:53]
	ds_read_b128 v[174:177], v194 offset:12288
	s_waitcnt lgkmcnt(1)
	v_mfma_f32_16x16x32_bf16 v[46:49], v[144:147], v[190:193], v[46:49]
	v_mfma_f32_16x16x32_bf16 v[42:45], v[178:181], v[190:193], v[42:45]
	v_mfma_f32_16x16x32_bf16 v[34:37], v[182:185], v[190:193], v[34:37]
	v_mfma_f32_16x16x32_bf16 v[30:33], v[186:189], v[190:193], v[30:33]
	ds_read_b128 v[190:193], v194 offset:14336
	s_waitcnt lgkmcnt(1)
	v_mfma_f32_16x16x32_bf16 v[194:197], v[144:147], v[174:177], v[26:29]
	s_nop 2
	v_add_u32_e32 v29, v156, v155
	ds_read_b128 v[198:201], v29
	ds_read_b128 v[202:205], v29 offset:2048
	ds_read_b128 v[206:209], v29 offset:4096
	ds_read_b128 v[210:213], v29 offset:6144
	v_add_u32_e32 v29, v157, v155
	v_mfma_f32_16x16x32_bf16 v[22:25], v[178:181], v[174:177], v[22:25]
	v_and_b32_e32 v28, 0xc0, v150
	v_lshl_or_b32 v153, v153, 2, v28
	v_lshlrev_b32_e32 v28, 3, v152
	v_mfma_f32_16x16x32_bf16 v[18:21], v[182:185], v[174:177], v[18:21]
	v_mad_i64_i32 v[26:27], s[22:23], s19, v149, v[172:173]
	v_lshl_add_u64 v[26:27], s[20:21], 1, v[26:27]
	v_mfma_f32_16x16x32_bf16 v[14:17], v[186:189], v[174:177], v[14:17]
	ds_read_b128 v[174:177], v29
	ds_read_b128 v[214:217], v29 offset:2048
	ds_read_b128 v[218:221], v29 offset:4096
	ds_read_b128 v[222:225], v29 offset:6144
	s_mov_b32 s19, 0
	s_waitcnt lgkmcnt(3)
	v_mfma_f32_16x16x32_bf16 v[126:129], v[198:201], v[174:177], v[126:129]
	v_mfma_f32_16x16x32_bf16 v[122:125], v[202:205], v[174:177], v[122:125]
	s_waitcnt lgkmcnt(1)
	v_mfma_f32_16x16x32_bf16 v[94:97], v[198:201], v[218:221], v[94:97]
	v_mfma_f32_16x16x32_bf16 v[10:13], v[144:147], v[190:193], v[10:13]
	ds_read_b128 v[144:147], v29 offset:8192
	ds_read_b128 v[226:229], v29 offset:10240
	ds_read_b128 v[230:233], v29 offset:12288
	ds_read_b128 v[234:237], v29 offset:14336
	v_lshlrev_b32_e32 v29, 9, v154
	v_and_or_b32 v152, v28, 8, v29
	v_mfma_f32_16x16x32_bf16 v[118:121], v[206:209], v[174:177], v[118:121]
	v_cvt_pk_bf16_f32 v28, v126, v127
	v_lshrrev_b32_e32 v126, 3, v153
	v_xor_b32_e32 v127, v126, v151
	v_mfma_f32_16x16x32_bf16 v[90:93], v[202:205], v[218:221], v[90:93]
	v_cvt_pk_bf16_f32 v29, v128, v129
	v_lshl_or_b32 v127, v127, 4, v152
	v_cvt_pk_bf16_f32 v122, v122, v123
	v_mfma_f32_16x16x32_bf16 v[114:117], v[210:213], v[174:177], v[114:117]
	v_cvt_pk_bf16_f32 v123, v124, v125
	v_bitop3_b32 v124, v126, v151, 2 bitop3:0x36
	v_cvt_pk_bf16_f32 v94, v94, v95
	v_mfma_f32_16x16x32_bf16 v[86:89], v[206:209], v[218:221], v[86:89]
	v_cvt_pk_bf16_f32 v95, v96, v97
	s_waitcnt lgkmcnt(0)
	s_barrier
; DEV unsigned cvt_pk_bf16(float lo, float hi) { const f32x2_t v = {lo, hi}; const bf16x2_t b = __builtin_convertvector(v, bf16x2_t); return __builtin_bit_cast(unsigned, b); }
; template <class Epi>
; DEV void gemm256_tile(const bf16_t* __restrict__ A, int lda, const bf16_t* __restrict__ Bt, int ldb, int K, unsigned char* lds, const Epi& epi) {
;     ...
;                 for (int mi = 0; mi < 4; ++mi)
; #pragma unroll
;                     for (int ni = 0; ni < 4; ++ni) acc[mh * 4 + mi][ni] = __builtin_amdgcn_mfma_f32_16x16x32_bf16(bfr[ni], af[mi], acc[mh * 4 + mi][ni], 0, 0, 0);
;             }
;         }
;     }
;     ...
;     __syncthreads();
;     if constexpr (Epi::STAGE) {
; #pragma unroll
;         for (int mi = 0; mi < 8; ++mi)
; #pragma unroll
;             for (int ni = 0; ni < 4; ++ni) {
;                 const int row = wr * 128 + mi * 16 + fr, col = wc * 64 + ni * 16 + fq * 4;
;                 const f32x4 v = epi.xform(row, col, acc[mi][ni]);
;                 uint2 w; w.x = cvt_pk_bf16(v[0], v[1]); w.y = cvt_pk_bf16(v[2], v[3]);
;                 *(uint2*)(lds + row * 512 + ((((col >> 3) ^ (row & 31)) << 4) | (((col >> 2) & 1) << 3))) = w;
;             }
;         __syncthreads();
	v_mfma_f32_16x16x32_bf16 v[110:113], v[198:201], v[214:217], v[110:113]
	v_lshl_add_u32 v124, v124, 4, v152
	v_cvt_pk_bf16_f32 v118, v118, v119
	v_mfma_f32_16x16x32_bf16 v[82:85], v[210:213], v[218:221], v[82:85]
	v_cvt_pk_bf16_f32 v119, v120, v121
	v_bitop3_b32 v120, v126, v151, 4 bitop3:0x36
	ds_write2st64_b64 v127, v[28:29], v[94:95] offset1:32
	v_mfma_f32_16x16x32_bf16 v[106:109], v[202:205], v[214:217], v[106:109]
	v_cvt_pk_bf16_f32 v28, v90, v91
	v_cvt_pk_bf16_f32 v29, v92, v93
	v_lshl_add_u32 v120, v120, 4, v152
	v_mfma_f32_16x16x32_bf16 v[78:81], v[198:201], v[222:225], v[78:81]
	v_cvt_pk_bf16_f32 v114, v114, v115
	v_cvt_pk_bf16_f32 v115, v116, v117
	v_bitop3_b32 v116, v126, v151, 6 bitop3:0x36
	v_mfma_f32_16x16x32_bf16 v[102:105], v[206:209], v[214:217], v[102:105]
	ds_write2st64_b64 v124, v[122:123], v[28:29] offset1:32
	v_cvt_pk_bf16_f32 v28, v86, v87
	v_cvt_pk_bf16_f32 v29, v88, v89
	v_mfma_f32_16x16x32_bf16 v[74:77], v[202:205], v[222:225], v[74:77]
	v_lshl_add_u32 v116, v116, 4, v152
	v_or_b32_e32 v117, 16, v151
	v_cvt_pk_bf16_f32 v110, v110, v111
	v_mfma_f32_16x16x32_bf16 v[2:5], v[182:185], v[190:193], v[2:5]
	v_cvt_pk_bf16_f32 v111, v112, v113
	v_bitop3_b32 v112, v126, v151, 16 bitop3:0x1e
	ds_write2st64_b64 v120, v[118:119], v[28:29] offset1:32
	v_mfma_f32_16x16x32_bf16 v[98:101], v[210:213], v[214:217], v[98:101]
	v_cvt_pk_bf16_f32 v28, v82, v83
	v_cvt_pk_bf16_f32 v29, v84, v85
	v_lshl_or_b32 v112, v112, 4, v152
	v_mfma_f32_16x16x32_bf16 v[70:73], v[206:209], v[222:225], v[70:73]
	v_cvt_pk_bf16_f32 v106, v106, v107
	v_cvt_pk_bf16_f32 v107, v108, v109
	v_bitop3_b32 v108, v126, v117, 2 bitop3:0x36
	v_mfma_f32_16x16x32_bf16 v[66:69], v[210:213], v[222:225], v[66:69]
	ds_write2st64_b64 v116, v[114:115], v[28:29] offset1:32
	v_cvt_pk_bf16_f32 v28, v78, v79
	v_cvt_pk_bf16_f32 v29, v80, v81
	v_lshl_add_u32 v108, v108, 4, v152
	v_cvt_pk_bf16_f32 v102, v102, v103
	v_cvt_pk_bf16_f32 v103, v104, v105
	v_bitop3_b32 v104, v126, v117, 4 bitop3:0x36
	ds_write2st64_b64 v112, v[110:111], v[28:29] offset0:16 offset1:48
	v_cvt_pk_bf16_f32 v28, v74, v75
	v_cvt_pk_bf16_f32 v29, v76, v77
	v_lshl_add_u32 v104, v104, 4, v152
	v_cvt_pk_bf16_f32 v98, v98, v99
	v_cvt_pk_bf16_f32 v99, v100, v101
	v_bitop3_b32 v100, v126, v117, 6 bitop3:0x36
	ds_write2st64_b64 v108, v[106:107], v[28:29] offset0:16 offset1:48
	v_cvt_pk_bf16_f32 v28, v70, v71
	v_cvt_pk_bf16_f32 v29, v72, v73
	v_mfma_f32_16x16x32_bf16 v[34:37], v[206:209], v[226:229], v[34:37]
	v_lshl_add_u32 v100, v100, 4, v152
	ds_write2st64_b64 v104, v[102:103], v[28:29] offset0:16 offset1:48
	v_cvt_pk_bf16_f32 v28, v66, v67
	v_mfma_f32_16x16x32_bf16 v[2:5], v[206:209], v[234:237], v[2:5]
	v_cvt_pk_bf16_f32 v29, v68, v69
	ds_write2st64_b64 v100, v[98:99], v[28:29] offset0:16 offset1:48
	s_nop 1
	v_cvt_pk_bf16_f32 v34, v34, v35
	v_mfma_f32_16x16x32_bf16 v[38:41], v[186:189], v[190:193], v[38:41]
	v_cvt_pk_bf16_f32 v35, v36, v37
	s_nop 0
	v_cvt_pk_bf16_f32 v2, v2, v3
	v_cvt_pk_bf16_f32 v3, v4, v5
	v_mfma_f32_16x16x32_bf16 v[6:9], v[178:181], v[190:193], v[6:9]
	ds_write2st64_b64 v104, v[34:35], v[2:3] offset0:80 offset1:112
	v_mfma_f32_16x16x32_bf16 v[28:31], v[210:213], v[226:229], v[30:33]
	v_mfma_f32_16x16x32_bf16 v[2:5], v[210:213], v[234:237], v[38:41]
	v_mfma_f32_16x16x32_bf16 v[62:65], v[198:201], v[144:147], v[62:65]
	s_nop 5
	v_cvt_pk_bf16_f32 v32, v28, v29
	v_cvt_pk_bf16_f32 v33, v30, v31
	v_cvt_pk_bf16_f32 v2, v2, v3
	v_mfma_f32_16x16x32_bf16 v[58:61], v[202:205], v[144:147], v[58:61]
	v_cvt_pk_bf16_f32 v3, v4, v5
	v_cvt_pk_bf16_f32 v62, v62, v63
	v_cvt_pk_bf16_f32 v63, v64, v65
	v_mfma_f32_16x16x32_bf16 v[54:57], v[206:209], v[144:147], v[54:57]
	ds_write2st64_b64 v100, v[32:33], v[2:3] offset0:80 offset1:112
	s_nop 2
	v_cvt_pk_bf16_f32 v58, v58, v59
	v_cvt_pk_bf16_f32 v59, v60, v61
	v_mfma_f32_16x16x32_bf16 v[50:53], v[210:213], v[144:147], v[50:53]
	v_and_b32_e32 v2, 0x1f0, v142
	v_cvt_pk_bf16_f32 v54, v54, v55
	v_cvt_pk_bf16_f32 v55, v56, v57
	v_mfma_f32_16x16x32_bf16 v[46:49], v[198:201], v[226:229], v[46:49]
	v_mfma_f32_16x16x32_bf16 v[42:45], v[202:205], v[226:229], v[42:45]
	s_nop 2
	v_cvt_pk_bf16_f32 v50, v50, v51
	v_cvt_pk_bf16_f32 v51, v52, v53
	s_nop 1
	v_cvt_pk_bf16_f32 v46, v46, v47
	v_mfma_f32_16x16x32_bf16 v[28:31], v[198:201], v[230:233], v[194:197]
	v_cvt_pk_bf16_f32 v47, v48, v49
	v_cvt_pk_bf16_f32 v42, v42, v43
	v_cvt_pk_bf16_f32 v43, v44, v45
	v_mfma_f32_16x16x32_bf16 v[22:25], v[202:205], v[230:233], v[22:25]
	v_mfma_f32_16x16x32_bf16 v[18:21], v[206:209], v[230:233], v[18:21]
	s_nop 2
	v_cvt_pk_bf16_f32 v28, v28, v29
	v_cvt_pk_bf16_f32 v29, v30, v31
	s_nop 1
	v_cvt_pk_bf16_f32 v22, v22, v23
	v_mfma_f32_16x16x32_bf16 v[14:17], v[210:213], v[230:233], v[14:17]
	v_cvt_pk_bf16_f32 v23, v24, v25
	v_cvt_pk_bf16_f32 v18, v18, v19
	v_cvt_pk_bf16_f32 v19, v20, v21
	v_mfma_f32_16x16x32_bf16 v[10:13], v[198:201], v[234:237], v[10:13]
	ds_write2st64_b64 v127, v[62:63], v[28:29] offset0:64 offset1:96
	s_nop 2
	v_cvt_pk_bf16_f32 v14, v14, v15
	v_cvt_pk_bf16_f32 v15, v16, v17
	v_mfma_f32_16x16x32_bf16 v[6:9], v[202:205], v[234:237], v[6:9]
	ds_write2st64_b64 v124, v[58:59], v[22:23] offset0:64 offset1:96
	v_cvt_pk_bf16_f32 v10, v10, v11
	v_cvt_pk_bf16_f32 v11, v12, v13
	ds_write2st64_b64 v120, v[54:55], v[18:19] offset0:64 offset1:96
	ds_write2st64_b64 v116, v[50:51], v[14:15] offset0:64 offset1:96
	s_nop 2
	v_cvt_pk_bf16_f32 v6, v6, v7
	v_cvt_pk_bf16_f32 v7, v8, v9
	ds_write2st64_b64 v112, v[46:47], v[10:11] offset0:80 offset1:112
	ds_write2st64_b64 v108, v[42:43], v[6:7] offset0:80 offset1:112
	s_waitcnt lgkmcnt(0)
	s_barrier

; __global__ void __launch_bounds__(512) hymba_fwd(Params p) {
;     ...
;             const int ob = bid - nsb, no = G - nsb;
;             for (int t0 = 2 * ob; t0 < NSM; t0 += 2 * no) gdn_sample_item(p, min(t0 + vb, NSM - 1), vlds);
;             for (int t0 = 2 * ob; t0 < NPL; t0 += 2 * no) { const int t = min(t0 + vb, NPL - 1); int nt, mt; tile_map(t, 68, 8, mt, nt); const int g = nt >> 1;
;                 EpiPoolS e{mt * 128, nt * 128, proj, p.in[15], mix + (size_t)mt * 128 * LDB + 1024 + nt * 128, LDB};
;                 gemm_tile<64>(dpl + (size_t)mt * 128 * LDP + g * 256, LDP, Wt_pool + (size_t)nt * 128 * LDM, LDM, 256, vlds, e);
.LBB0_868:
	s_cmpk_gt_u32 s35, 0x10f
	s_cbranch_scc1 .LBB0_871
	s_load_dwordx2 s[4:5], s[0:1], 0x78
	v_and_b32_e32 v1, 0xff, v0
	s_add_i32 s73, s70, 0x8000
	s_lshl_b32 s74, s31, 1
	s_movk_i32 s76, 0xffc0
	v_mov_b32_e32 v134, 0x84000
	v_mov_b32_e32 v135, 0x44000
	v_mov_b32_e32 v136, 0x12000
	s_movk_i32 s77, 0x880
	v_mov_b32_e32 v131, 0
	s_movk_i32 s78, 0x240
	s_mov_b64 s[6:7], 0x11000
	s_mov_b64 s[8:9], 0x4800
	s_mov_b64 s[10:11], 0x22000
	s_mov_b64 s[12:13], 0x9000
	s_mov_b64 s[16:17], 0x33000
	s_movk_i32 s79, 0x3000
	s_mov_b64 s[18:19], 0xd800
	s_mov_b64 s[20:21], 0x80
	s_mov_b64 s[22:23], 0x11080
	s_mov_b64 s[24:25], 0x4880
	s_mov_b64 s[26:27], 0x22080
	s_mov_b64 s[30:31], 0x9080
	s_mov_b64 s[34:35], 0x33080
	s_mov_b64 s[36:37], 0xd880
	s_mov_b64 s[38:39], 0x100
	s_mov_b64 s[40:41], 0x11100
	s_mov_b64 s[42:43], 0x4900
	s_mov_b64 s[44:45], 0x22100
	s_mov_b64 s[46:47], 0x9100
	s_mov_b64 s[48:49], 0x33100
	s_mov_b64 s[50:51], 0xd900
	s_mov_b64 s[52:53], 0x180
	s_mov_b64 s[54:55], 0x11180
	s_mov_b64 s[56:57], 0x4980
	s_mov_b64 s[58:59], 0x22180
	s_mov_b64 s[60:61], 0x9180
	s_mov_b64 s[62:63], 0x33180
	s_mov_b64 s[64:65], 0xd980
	s_mov_b64 s[66:67], 0x2800
	s_movk_i32 s80, 0x1080

; DEV void gdn_scan_item(const Params& p, int item, unsigned char* lds) {
;     ...
;     LOAD_E(E0, 0); LOAD_L(L0, 0); LOAD_E(E1, 1);
;     __syncthreads();
;     for (int ch = 0; ch < 30; ch += 6) {
;         SCAN_STEP(E0, E2, L0, L1, ch);     SCAN_STEP(E1, E0, L1, L0, ch + 1); SCAN_STEP(E2, E1, L0, L1, ch + 2);
;         SCAN_STEP(E0, E2, L1, L0, ch + 3); SCAN_STEP(E1, E0, L0, L1, ch + 4); SCAN_STEP(E2, E1, L1, L0, ch + 5);
;     }
.LBB0_888:
	v_lshl_add_u64 v[214:215], s[8:9], 0, v[196:197]
	v_add_co_u32_e32 v98, vcc, s25, v214
	v_lshl_add_u64 v[216:217], s[8:9], 0, v[198:199]
	s_nop 0
	v_addc_co_u32_e32 v99, vcc, 0, v215, vcc
	v_add_co_u32_e32 v102, vcc, s26, v214
	v_lshl_add_u64 v[218:219], s[8:9], 0, v[200:201]
	s_nop 0
	v_addc_co_u32_e32 v103, vcc, 0, v215, vcc
	v_add_co_u32_e32 v106, vcc, s25, v216
	v_lshl_add_u64 v[220:221], s[8:9], 0, v[202:203]
	s_nop 0
	v_addc_co_u32_e32 v107, vcc, 0, v217, vcc
	v_add_co_u32_e32 v110, vcc, s26, v216
	v_lshl_add_u64 v[222:223], s[8:9], 0, v[194:195]
	s_nop 0
	v_addc_co_u32_e32 v111, vcc, 0, v217, vcc
	v_add_co_u32_e32 v114, vcc, s25, v218
	v_lshl_add_u64 v[224:225], s[8:9], 0, v[204:205]
	s_nop 0
	v_addc_co_u32_e32 v115, vcc, 0, v219, vcc
	v_add_co_u32_e32 v118, vcc, s26, v218
	global_load_dwordx4 v[98:101], v[98:99], off
	s_nop 0
	v_addc_co_u32_e32 v119, vcc, 0, v219, vcc
	v_add_co_u32_e32 v122, vcc, s25, v220
	global_load_dwordx4 v[102:105], v[102:103], off
	s_nop 0
	v_addc_co_u32_e32 v123, vcc, 0, v221, vcc
	v_add_co_u32_e32 v126, vcc, s26, v220
	global_load_dwordx4 v[106:109], v[106:107], off
	s_nop 0
	v_addc_co_u32_e32 v127, vcc, 0, v221, vcc
	v_add_co_u32_e32 v130, vcc, s27, v222
	global_load_dwordx4 v[110:113], v[110:111], off
	s_nop 0
	v_addc_co_u32_e32 v131, vcc, 0, v223, vcc
	global_load_dwordx4 v[114:117], v[114:115], off
	v_lshl_add_u64 v[226:227], s[8:9], 0, v[206:207]
	global_load_dwordx4 v[118:121], v[118:119], off
	v_lshl_add_u64 v[228:229], s[8:9], 0, v[208:209]
	global_load_dwordx4 v[122:125], v[122:123], off
	v_lshl_add_u64 v[230:231], s[8:9], 0, v[210:211]
	global_load_dwordx4 v[126:129], v[126:127], off
	s_nop 0
	global_load_dword v241, v[130:131], off
	global_load_dword v242, v[130:131], off offset:256
	global_load_dword v243, v[130:131], off offset:512
	global_load_dword v244, v[130:131], off offset:768
	v_add_co_u32_e32 v130, vcc, s34, v224
	v_lshl_add_u64 v[232:233], s[8:9], 0, v[212:213]
	s_nop 0
	v_addc_co_u32_e32 v131, vcc, 0, v225, vcc
	v_add_co_u32_e32 v134, vcc, s34, v226
	global_load_dwordx4 v[130:133], v[130:131], off
	s_nop 0
	v_addc_co_u32_e32 v135, vcc, 0, v227, vcc
	v_add_co_u32_e32 v146, vcc, s35, v228
	global_load_dwordx4 v[134:137], v[134:135], off
	s_nop 0
	v_addc_co_u32_e32 v147, vcc, 0, v229, vcc
	v_add_co_u32_e32 v142, vcc, s35, v230
	global_load_dwordx4 v[138:141], v[146:147], off
	s_nop 0
	v_addc_co_u32_e32 v143, vcc, 0, v231, vcc
	global_load_dwordx4 v[142:145], v[142:143], off
	s_nop 0
	global_load_dwordx4 v[146:149], v[146:147], off offset:1024
	ds_read_b128 v[246:249], v237
	s_waitcnt vmcnt(37) lgkmcnt(0)
	v_mfma_f32_16x16x32_bf16 v[18:21], v[18:21], v[246:249], 0
	v_add_co_u32_e32 v150, vcc, s35, v232
	s_add_i32 s61, s62, 6
	s_waitcnt vmcnt(31)
	v_mfma_f32_16x16x32_bf16 v[38:41], v[38:41], v[246:249], 0
	ds_read_b128 v[246:249], v237 offset:64
	v_addc_co_u32_e32 v151, vcc, 0, v233, vcc
	s_waitcnt lgkmcnt(0)
	v_mfma_f32_16x16x32_bf16 v[6:9], v[6:9], v[246:249], v[18:21]
	global_load_dwordx4 v[150:153], v[150:151], off
	s_nop 1
	ds_read_b128 v[18:21], v237 offset:128
	s_add_i32 s65, s62, 7
	v_mfma_f32_16x16x32_bf16 v[2:5], v[2:5], v[246:249], v[38:41]
	v_readlane_b32 s64, v177, s61
	v_readlane_b32 s66, v177, s65
	s_add_i32 s63, s62, 8
	s_waitcnt vmcnt(27) lgkmcnt(0)
	v_mfma_f32_16x16x32_bf16 v[2:5], v[14:17], v[18:21], v[2:5]
	ds_read_b128 v[14:17], v237 offset:192
	v_lshl_add_u64 v[194:195], v[194:195], 0, s[16:17]
	v_lshl_add_u64 v[196:197], v[196:197], 0, s[18:19]
	s_waitcnt vmcnt(21)
	v_mfma_f32_16x16x32_bf16 v[6:9], v[26:29], v[18:21], v[6:9]
	v_mul_f32_e64 v20, v92, s64
	v_mul_f32_e64 v21, v93, s64
	v_pk_mul_f32 v[18:19], v[90:91], s[64:65] op_sel_hi:[1,0]
	v_lshl_add_u64 v[198:199], v[198:199], 0, s[18:19]
	s_waitcnt vmcnt(19) lgkmcnt(0)
	v_mfma_f32_16x16x32_bf16 v[6:9], v[22:25], v[14:17], v[6:9]
	v_lshl_add_u64 v[200:201], v[200:201], 0, s[18:19]
	v_lshl_add_u64 v[202:203], v[202:203], 0, s[18:19]
	v_lshl_add_u64 v[204:205], v[204:205], 0, s[20:21]
	v_mfma_f32_16x16x32_bf16 v[2:5], v[10:13], v[14:17], v[2:5]
	v_mul_f32_e64 v16, v96, s64
	v_mul_f32_e64 v17, v97, s64
	s_nop 1
	v_sub_f32_e32 v9, v240, v9
	v_sub_f32_e32 v8, v239, v8
	v_sub_f32_e32 v7, v238, v7
	v_sub_f32_e32 v6, v193, v6
	v_cvt_pk_bf16_f32 v6, v6, v7
	v_cvt_pk_bf16_f32 v7, v8, v9
	ds_write_b64 v236, v[6:7] offset:4352
	s_waitcnt lgkmcnt(0)
	s_barrier
	ds_read_b128 v[6:9], v235 offset:4352
	ds_read_b128 v[10:13], v235 offset:4416
	v_pk_mul_f32 v[14:15], v[94:95], s[64:65] op_sel_hi:[1,0]
	s_waitcnt lgkmcnt(1)
	v_mfma_f32_16x16x32_bf16 v[2:5], v[86:89], v[6:9], v[2:5]
	v_ashrrev_i32_e32 v193, 31, v192
	s_add_i32 s64, s62, 9
	s_add_i32 s65, s62, 10
	v_mfma_f32_16x16x32_bf16 v[14:17], v[70:73], v[6:9], v[14:17]
	v_readlane_b32 s64, v177, s64
	s_add_i32 s62, s62, 11
	v_readlane_b32 s62, v177, s62
	v_mfma_f32_16x16x32_bf16 v[6:9], v[66:69], v[6:9], v[18:21]
	v_lshl_add_u64 v[206:207], v[206:207], 0, s[20:21]
	v_lshl_add_u64 v[208:209], v[208:209], 0, s[18:19]
	v_lshl_add_u64 v[210:211], v[210:211], 0, s[18:19]
	s_waitcnt lgkmcnt(0)
	v_mfma_f32_16x16x32_bf16 v[90:93], v[82:85], v[10:13], v[14:17]
	v_lshl_add_u64 v[212:213], v[212:213], 0, s[18:19]
	s_cmp_lt_u32 s61, 24
	v_mfma_f32_16x16x32_bf16 v[94:97], v[78:81], v[10:13], v[6:9]
	v_mfma_f32_16x16x32_bf16 v[2:5], v[74:77], v[10:13], v[2:5]
	s_nop 3
	v_cvt_pk_bf16_f32 v6, v90, v91
	v_cvt_pk_bf16_f32 v7, v92, v93
	s_nop 0
	v_cvt_pk_bf16_f32 v8, v94, v95
	v_cvt_pk_bf16_f32 v9, v96, v97
	ds_write2_b64 v234, v[6:7], v[8:9] offset1:4
	v_lshlrev_b64 v[6:7], 12, v[192:193]
	v_lshl_add_u64 v[6:7], v[190:191], 0, v[6:7]
	v_add_co_u32_e32 v8, vcc, s30, v6
	global_store_dword v[6:7], v2, off
	s_nop 0
	v_addc_co_u32_e32 v9, vcc, 0, v7, vcc
	v_add_co_u32_e32 v2, vcc, s31, v6
	global_store_dword v[8:9], v3, off offset:-4096
	global_store_dword v[8:9], v4, off
	v_addc_co_u32_e32 v3, vcc, 0, v7, vcc
	global_store_dword v[2:3], v5, off
	v_add_co_u32_e32 v2, vcc, s36, v214
	s_waitcnt lgkmcnt(0)
	s_barrier
; DEV void gdn_scan_item(const Params& p, int item, unsigned char* lds) {
;     ...
;     LOAD_E(E0, 0); LOAD_L(L0, 0); LOAD_E(E1, 1);
;     __syncthreads();
;     for (int ch = 0; ch < 30; ch += 6) {
;         SCAN_STEP(E0, E2, L0, L1, ch);     SCAN_STEP(E1, E0, L1, L0, ch + 1); SCAN_STEP(E2, E1, L0, L1, ch + 2);
;         SCAN_STEP(E0, E2, L1, L0, ch + 3); SCAN_STEP(E1, E0, L0, L1, ch + 4); SCAN_STEP(E2, E1, L1, L0, ch + 5);
;     }
	s_nop 0
	v_addc_co_u32_e32 v3, vcc, 0, v215, vcc
	v_add_co_u32_e32 v6, vcc, s37, v214
	global_load_dwordx4 v[2:5], v[2:3], off
	s_nop 0
	v_addc_co_u32_e32 v7, vcc, 0, v215, vcc
	v_add_co_u32_e32 v10, vcc, s36, v216
	global_load_dwordx4 v[6:9], v[6:7], off
	s_nop 0
	v_addc_co_u32_e32 v11, vcc, 0, v217, vcc
	v_add_co_u32_e32 v14, vcc, s37, v216
	global_load_dwordx4 v[10:13], v[10:11], off
	s_nop 0
	v_addc_co_u32_e32 v15, vcc, 0, v217, vcc
	v_add_co_u32_e32 v18, vcc, s36, v218
	global_load_dwordx4 v[14:17], v[14:15], off
	s_nop 0
	v_addc_co_u32_e32 v19, vcc, 0, v219, vcc
	v_add_co_u32_e32 v22, vcc, s37, v218
	global_load_dwordx4 v[18:21], v[18:19], off
	s_nop 0
	v_addc_co_u32_e32 v23, vcc, 0, v219, vcc
	v_add_co_u32_e32 v26, vcc, s36, v220
	global_load_dwordx4 v[22:25], v[22:23], off
	s_nop 0
	v_addc_co_u32_e32 v27, vcc, 0, v221, vcc
	v_add_co_u32_e32 v38, vcc, s37, v220
	global_load_dwordx4 v[26:29], v[26:27], off
	s_nop 0
	v_addc_co_u32_e32 v39, vcc, 0, v221, vcc
	v_add_co_u32_e32 v66, vcc, s38, v222
	global_load_dwordx4 v[38:41], v[38:39], off
	s_nop 0
	v_addc_co_u32_e32 v67, vcc, 0, v223, vcc
	global_load_dword v193, v[66:67], off
	global_load_dword v238, v[66:67], off offset:256
	global_load_dword v239, v[66:67], off offset:512
	global_load_dword v240, v[66:67], off offset:768
	v_add_co_u32_e32 v66, vcc, s39, v224
	s_nop 1
	v_addc_co_u32_e32 v67, vcc, 0, v225, vcc
	v_add_co_u32_e32 v70, vcc, s39, v226
	global_load_dwordx4 v[66:69], v[66:67], off
	s_nop 0
	v_addc_co_u32_e32 v71, vcc, 0, v227, vcc
	v_add_co_u32_e32 v82, vcc, s40, v228
	global_load_dwordx4 v[74:77], v[70:71], off
	s_nop 0
	v_addc_co_u32_e32 v83, vcc, 0, v229, vcc
	v_add_co_u32_e32 v78, vcc, s40, v230
	global_load_dwordx4 v[70:73], v[82:83], off
	s_nop 0
	v_addc_co_u32_e32 v79, vcc, 0, v231, vcc
	global_load_dwordx4 v[78:81], v[78:79], off
	s_nop 0
	global_load_dwordx4 v[82:85], v[82:83], off offset:1024
	ds_read_b128 v[246:249], v237
	s_waitcnt lgkmcnt(0)
	v_mfma_f32_16x16x32_bf16 v[30:33], v[30:33], v[246:249], 0
	v_add_co_u32_e32 v86, vcc, s40, v232
	v_mfma_f32_16x16x32_bf16 v[34:37], v[34:37], v[246:249], 0
	ds_read_b128 v[246:249], v237 offset:64
	v_addc_co_u32_e32 v87, vcc, 0, v233, vcc
	s_waitcnt lgkmcnt(0)
	v_mfma_f32_16x16x32_bf16 v[30:33], v[46:49], v[246:249], v[30:33]
	ds_read_b128 v[46:49], v237 offset:128
	global_load_dwordx4 v[86:89], v[86:87], off
	s_waitcnt lgkmcnt(0)
	v_mfma_f32_16x16x32_bf16 v[30:33], v[42:45], v[46:49], v[30:33]
	ds_read_b128 v[42:45], v237 offset:192
	v_mfma_f32_16x16x32_bf16 v[34:37], v[50:53], v[246:249], v[34:37]
	v_mul_f32_e64 v52, v96, s66
	v_mul_f32_e64 v53, v97, s66
	v_pk_mul_f32 v[50:51], v[94:95], s[66:67] op_sel_hi:[1,0]
	s_waitcnt lgkmcnt(0)
	v_mfma_f32_16x16x32_bf16 v[30:33], v[58:61], v[42:45], v[30:33]
	v_mfma_f32_16x16x32_bf16 v[34:37], v[54:57], v[46:49], v[34:37]
	v_mul_f32_e64 v48, v92, s66
	v_mul_f32_e64 v49, v93, s66
	s_nop 4
	v_sub_f32_e32 v33, v156, v33
	v_sub_f32_e32 v32, v155, v32
	v_sub_f32_e32 v31, v154, v31
	s_waitcnt vmcnt(40)
	v_sub_f32_e32 v30, v157, v30
	v_cvt_pk_bf16_f32 v30, v30, v31
	v_cvt_pk_bf16_f32 v31, v32, v33
	ds_write_b64 v236, v[30:31] offset:4352
	s_waitcnt lgkmcnt(0)
	s_barrier
	v_mfma_f32_16x16x32_bf16 v[34:37], v[62:65], v[42:45], v[34:37]
	ds_read_b128 v[30:33], v235 offset:4352
	ds_read_b128 v[42:45], v235 offset:4416
	v_pk_mul_f32 v[46:47], v[90:91], s[66:67] op_sel_hi:[1,0]
	v_readlane_b32 s66, v177, s63
	s_waitcnt vmcnt(27) lgkmcnt(1)
	v_mfma_f32_16x16x32_bf16 v[34:37], v[130:133], v[30:33], v[34:37]
	s_waitcnt vmcnt(25)
	v_mfma_f32_16x16x32_bf16 v[46:49], v[138:141], v[30:33], v[46:49]
	s_waitcnt vmcnt(23)
	v_mfma_f32_16x16x32_bf16 v[30:33], v[146:149], v[30:33], v[50:53]
	s_waitcnt lgkmcnt(0)
	v_mfma_f32_16x16x32_bf16 v[90:93], v[142:145], v[42:45], v[46:49]
	s_waitcnt vmcnt(22)
	v_mfma_f32_16x16x32_bf16 v[94:97], v[150:153], v[42:45], v[30:33]
	v_mfma_f32_16x16x32_bf16 v[34:37], v[134:137], v[42:45], v[34:37]
	s_nop 4
	v_cvt_pk_bf16_f32 v30, v90, v91
	v_cvt_pk_bf16_f32 v31, v92, v93
	v_cvt_pk_bf16_f32 v32, v94, v95
	v_cvt_pk_bf16_f32 v33, v96, v97
	ds_write2_b64 v234, v[30:31], v[32:33] offset1:4
	v_add_u32_e32 v30, 64, v192
	v_ashrrev_i32_e32 v31, 31, v30
	v_lshlrev_b64 v[30:31], 12, v[30:31]
	v_lshl_add_u64 v[30:31], v[190:191], 0, v[30:31]
	v_add_co_u32_e32 v32, vcc, s30, v30
	global_store_dword v[30:31], v34, off
	s_nop 0
	v_addc_co_u32_e32 v33, vcc, 0, v31, vcc
	v_add_co_u32_e32 v30, vcc, s31, v30
	global_store_dword v[32:33], v35, off offset:-4096
	global_store_dword v[32:33], v36, off
	v_addc_co_u32_e32 v31, vcc, 0, v31, vcc
	global_store_dword v[30:31], v37, off
	v_add_co_u32_e32 v30, vcc, s41, v214
	s_waitcnt lgkmcnt(0)
	s_barrier
; DEV void gdn_scan_item(const Params& p, int item, unsigned char* lds) {
;     ...
;     LOAD_E(E0, 0); LOAD_L(L0, 0); LOAD_E(E1, 1);
;     __syncthreads();
;     for (int ch = 0; ch < 30; ch += 6) {
;         SCAN_STEP(E0, E2, L0, L1, ch);     SCAN_STEP(E1, E0, L1, L0, ch + 1); SCAN_STEP(E2, E1, L0, L1, ch + 2);
;         SCAN_STEP(E0, E2, L1, L0, ch + 3); SCAN_STEP(E1, E0, L0, L1, ch + 4); SCAN_STEP(E2, E1, L1, L0, ch + 5);
;     }
	s_nop 0
	v_addc_co_u32_e32 v31, vcc, 0, v215, vcc
	v_add_co_u32_e32 v34, vcc, s42, v214
	global_load_dwordx4 v[30:33], v[30:31], off
	s_nop 0
	v_addc_co_u32_e32 v35, vcc, 0, v215, vcc
	v_add_co_u32_e32 v42, vcc, s41, v216
	global_load_dwordx4 v[34:37], v[34:35], off
	s_nop 0
	v_addc_co_u32_e32 v43, vcc, 0, v217, vcc
	v_add_co_u32_e32 v46, vcc, s42, v216
	global_load_dwordx4 v[42:45], v[42:43], off
	s_nop 0
	v_addc_co_u32_e32 v47, vcc, 0, v217, vcc
	v_add_co_u32_e32 v50, vcc, s41, v218
	global_load_dwordx4 v[46:49], v[46:47], off
	s_nop 0
	v_addc_co_u32_e32 v51, vcc, 0, v219, vcc
	v_add_co_u32_e32 v54, vcc, s42, v218
	global_load_dwordx4 v[50:53], v[50:51], off
	s_nop 0
	v_addc_co_u32_e32 v55, vcc, 0, v219, vcc
	v_add_co_u32_e32 v58, vcc, s41, v220
	global_load_dwordx4 v[54:57], v[54:55], off
	s_nop 0
	v_addc_co_u32_e32 v59, vcc, 0, v221, vcc
	v_add_co_u32_e32 v62, vcc, s42, v220
	global_load_dwordx4 v[58:61], v[58:59], off
	s_nop 0
	v_addc_co_u32_e32 v63, vcc, 0, v221, vcc
	v_add_co_u32_e32 v130, vcc, s43, v222
	global_load_dwordx4 v[62:65], v[62:63], off
	s_nop 0
	v_addc_co_u32_e32 v131, vcc, 0, v223, vcc
	global_load_dword v245, v[130:131], off
	global_load_dword v246, v[130:131], off offset:256
	global_load_dword v247, v[130:131], off offset:512
	global_load_dword v248, v[130:131], off offset:768
	v_add_co_u32_e32 v130, vcc, s44, v224
	s_nop 1
	v_addc_co_u32_e32 v131, vcc, 0, v225, vcc
	v_add_co_u32_e32 v134, vcc, s44, v226
	global_load_dwordx4 v[130:133], v[130:131], off
	s_nop 0
	v_addc_co_u32_e32 v135, vcc, 0, v227, vcc
	v_add_co_u32_e32 v146, vcc, s45, v228
	global_load_dwordx4 v[138:141], v[134:135], off
	s_nop 0
	v_addc_co_u32_e32 v147, vcc, 0, v229, vcc
	v_add_co_u32_e32 v142, vcc, s45, v230
	global_load_dwordx4 v[134:137], v[146:147], off
	s_nop 0
	v_addc_co_u32_e32 v143, vcc, 0, v231, vcc
	global_load_dwordx4 v[142:145], v[142:143], off
	s_nop 0
	global_load_dwordx4 v[146:149], v[146:147], off offset:1024
	ds_read_b128 v[154:157], v237
	s_waitcnt lgkmcnt(0)
	v_mfma_f32_16x16x32_bf16 v[98:101], v[98:101], v[154:157], 0
	v_add_co_u32_e32 v150, vcc, s45, v232
	v_mfma_f32_16x16x32_bf16 v[102:105], v[102:105], v[154:157], 0
	ds_read_b128 v[154:157], v237 offset:64
	v_addc_co_u32_e32 v151, vcc, 0, v233, vcc
	s_waitcnt lgkmcnt(0)
	v_mfma_f32_16x16x32_bf16 v[98:101], v[106:109], v[154:157], v[98:101]
	ds_read_b128 v[106:109], v237 offset:128
	global_load_dwordx4 v[150:153], v[150:151], off
	v_mfma_f32_16x16x32_bf16 v[102:105], v[110:113], v[154:157], v[102:105]
	s_waitcnt lgkmcnt(0)
	v_mfma_f32_16x16x32_bf16 v[98:101], v[114:117], v[106:109], v[98:101]
	v_mfma_f32_16x16x32_bf16 v[102:105], v[118:121], v[106:109], v[102:105]
	ds_read_b128 v[106:109], v237 offset:192
	s_waitcnt lgkmcnt(0)
	v_mfma_f32_16x16x32_bf16 v[98:101], v[122:125], v[106:109], v[98:101]
	v_mfma_f32_16x16x32_bf16 v[102:105], v[126:129], v[106:109], v[102:105]
	s_nop 6
	v_sub_f32_e32 v101, v244, v101
	v_sub_f32_e32 v100, v243, v100
	v_sub_f32_e32 v99, v242, v99
	v_sub_f32_e32 v98, v241, v98
	v_cvt_pk_bf16_f32 v98, v98, v99
	v_cvt_pk_bf16_f32 v99, v100, v101
	ds_write_b64 v236, v[98:99] offset:4352
	s_waitcnt lgkmcnt(0)
	s_barrier
	ds_read_b128 v[98:101], v235 offset:4352
	ds_read_b128 v[106:109], v235 offset:4416
	s_waitcnt vmcnt(27) lgkmcnt(1)
	v_mfma_f32_16x16x32_bf16 v[66:69], v[66:69], v[98:101], v[102:105]
	s_waitcnt vmcnt(26) lgkmcnt(0)
	v_mfma_f32_16x16x32_bf16 v[66:69], v[74:77], v[106:109], v[66:69]
	v_mul_f32_e64 v76, v92, s66
	v_mul_f32_e64 v77, v93, s66
	v_pk_mul_f32 v[74:75], v[90:91], s[66:67] op_sel_hi:[1,0]
	v_pk_mul_f32 v[92:93], v[96:97], s[66:67] op_sel_hi:[1,0]
	v_pk_mul_f32 v[90:91], v[94:95], s[66:67] op_sel_hi:[1,0]
	s_waitcnt vmcnt(25)
	v_mfma_f32_16x16x32_bf16 v[70:73], v[70:73], v[98:101], v[74:77]
	s_waitcnt vmcnt(24)
	v_mfma_f32_16x16x32_bf16 v[122:125], v[78:81], v[106:109], v[70:73]
	s_waitcnt vmcnt(23)
	v_mfma_f32_16x16x32_bf16 v[70:73], v[82:85], v[98:101], v[90:93]
	s_waitcnt vmcnt(22)
	v_mfma_f32_16x16x32_bf16 v[126:129], v[86:89], v[106:109], v[70:73]
	s_nop 5
	v_cvt_pk_bf16_f32 v70, v122, v123
	v_cvt_pk_bf16_f32 v71, v124, v125
	v_cvt_pk_bf16_f32 v72, v126, v127
	v_cvt_pk_bf16_f32 v73, v128, v129
	ds_write2_b64 v234, v[70:71], v[72:73] offset1:4
	v_add_u32_e32 v70, 0x80, v192
	v_ashrrev_i32_e32 v71, 31, v70
	v_lshlrev_b64 v[70:71], 12, v[70:71]
	v_lshl_add_u64 v[70:71], v[190:191], 0, v[70:71]
	v_add_co_u32_e32 v72, vcc, s30, v70
	global_store_dword v[70:71], v66, off
	s_nop 0
	v_addc_co_u32_e32 v73, vcc, 0, v71, vcc
	v_add_co_u32_e32 v66, vcc, s31, v70
	global_store_dword v[72:73], v67, off offset:-4096
	global_store_dword v[72:73], v68, off
	v_addc_co_u32_e32 v67, vcc, 0, v71, vcc
	global_store_dword v[66:67], v69, off
	v_add_co_u32_e32 v66, vcc, s46, v214
	s_waitcnt lgkmcnt(0)
	s_barrier
; DEV void gdn_scan_item(const Params& p, int item, unsigned char* lds) {
;     ...
;     LOAD_E(E0, 0); LOAD_L(L0, 0); LOAD_E(E1, 1);
;     __syncthreads();
;     for (int ch = 0; ch < 30; ch += 6) {
;         SCAN_STEP(E0, E2, L0, L1, ch);     SCAN_STEP(E1, E0, L1, L0, ch + 1); SCAN_STEP(E2, E1, L0, L1, ch + 2);
;         SCAN_STEP(E0, E2, L1, L0, ch + 3); SCAN_STEP(E1, E0, L0, L1, ch + 4); SCAN_STEP(E2, E1, L1, L0, ch + 5);
;     }
	s_nop 0
	v_addc_co_u32_e32 v67, vcc, 0, v215, vcc
	global_load_dwordx4 v[90:93], v[66:67], off
	v_add_co_u32_e32 v66, vcc, s47, v214
	s_nop 1
	v_addc_co_u32_e32 v67, vcc, 0, v215, vcc
	global_load_dwordx4 v[94:97], v[66:67], off
	v_add_co_u32_e32 v66, vcc, s46, v216
	s_nop 1
	v_addc_co_u32_e32 v67, vcc, 0, v217, vcc
	global_load_dwordx4 v[98:101], v[66:67], off
	v_add_co_u32_e32 v66, vcc, s47, v216
	s_nop 1
	v_addc_co_u32_e32 v67, vcc, 0, v217, vcc
	global_load_dwordx4 v[102:105], v[66:67], off
	v_add_co_u32_e32 v66, vcc, s46, v218
	s_nop 1
	v_addc_co_u32_e32 v67, vcc, 0, v219, vcc
	global_load_dwordx4 v[106:109], v[66:67], off
	v_add_co_u32_e32 v66, vcc, s47, v218
	s_nop 1
	v_addc_co_u32_e32 v67, vcc, 0, v219, vcc
	global_load_dwordx4 v[110:113], v[66:67], off
	v_add_co_u32_e32 v66, vcc, s46, v220
	s_nop 1
	v_addc_co_u32_e32 v67, vcc, 0, v221, vcc
	global_load_dwordx4 v[114:117], v[66:67], off
	v_add_co_u32_e32 v66, vcc, s47, v220
	s_nop 1
	v_addc_co_u32_e32 v67, vcc, 0, v221, vcc
	global_load_dwordx4 v[118:121], v[66:67], off
	v_add_co_u32_e32 v66, vcc, s48, v222
	s_nop 1
	v_addc_co_u32_e32 v67, vcc, 0, v223, vcc
	global_load_dword v241, v[66:67], off
	global_load_dword v242, v[66:67], off offset:256
	global_load_dword v243, v[66:67], off offset:512
	global_load_dword v244, v[66:67], off offset:768
	v_add_co_u32_e32 v66, vcc, s49, v224
	s_nop 1
	v_addc_co_u32_e32 v67, vcc, 0, v225, vcc
	v_add_co_u32_e32 v70, vcc, s49, v226
	global_load_dwordx4 v[66:69], v[66:67], off
	s_nop 0
	v_addc_co_u32_e32 v71, vcc, 0, v227, vcc
	v_add_co_u32_e32 v82, vcc, s50, v228
	global_load_dwordx4 v[74:77], v[70:71], off
	s_nop 0
	v_addc_co_u32_e32 v83, vcc, 0, v229, vcc
	v_add_co_u32_e32 v78, vcc, s50, v230
	global_load_dwordx4 v[70:73], v[82:83], off
	s_nop 0
	v_addc_co_u32_e32 v79, vcc, 0, v231, vcc
	global_load_dwordx4 v[78:81], v[78:79], off
	s_nop 0
	global_load_dwordx4 v[82:85], v[82:83], off offset:1024
	ds_read_b128 v[154:157], v237
	s_waitcnt lgkmcnt(0)
	v_mfma_f32_16x16x32_bf16 v[2:5], v[2:5], v[154:157], 0
	v_add_co_u32_e32 v86, vcc, s50, v232
	v_mfma_f32_16x16x32_bf16 v[6:9], v[6:9], v[154:157], 0
	ds_read_b128 v[154:157], v237 offset:64
	v_addc_co_u32_e32 v87, vcc, 0, v233, vcc
	s_waitcnt lgkmcnt(0)
	v_mfma_f32_16x16x32_bf16 v[2:5], v[10:13], v[154:157], v[2:5]
	ds_read_b128 v[10:13], v237 offset:128
	global_load_dwordx4 v[86:89], v[86:87], off
	v_mfma_f32_16x16x32_bf16 v[6:9], v[14:17], v[154:157], v[6:9]
	s_waitcnt lgkmcnt(0)
	v_mfma_f32_16x16x32_bf16 v[2:5], v[18:21], v[10:13], v[2:5]
	v_mul_f32_e64 v20, v128, s64
	v_mul_f32_e64 v21, v129, s64
	v_pk_mul_f32 v[18:19], v[126:127], s[64:65] op_sel_hi:[1,0]
	v_mfma_f32_16x16x32_bf16 v[6:9], v[22:25], v[10:13], v[6:9]
	ds_read_b128 v[10:13], v237 offset:192
	s_waitcnt lgkmcnt(0)
	v_mfma_f32_16x16x32_bf16 v[2:5], v[26:29], v[10:13], v[2:5]
	v_mfma_f32_16x16x32_bf16 v[6:9], v[38:41], v[10:13], v[6:9]
	s_nop 6
	v_sub_f32_e32 v5, v240, v5
	v_sub_f32_e32 v4, v239, v4
	v_sub_f32_e32 v3, v238, v3
	v_sub_f32_e32 v2, v193, v2
	v_cvt_pk_bf16_f32 v2, v2, v3
	v_cvt_pk_bf16_f32 v3, v4, v5
	ds_write_b64 v236, v[2:3] offset:4352
	s_waitcnt lgkmcnt(0)
	s_barrier
	ds_read_b128 v[10:13], v235 offset:4352
	ds_read_b128 v[14:17], v235 offset:4416
	s_waitcnt vmcnt(27) lgkmcnt(1)
	v_mfma_f32_16x16x32_bf16 v[2:5], v[130:133], v[10:13], v[6:9]
	s_nop 2
	v_mul_f32_e64 v8, v124, s64
	v_mul_f32_e64 v9, v125, s64
	v_pk_mul_f32 v[6:7], v[122:123], s[64:65] op_sel_hi:[1,0]
	v_readlane_b32 s64, v177, s65
	s_waitcnt vmcnt(26) lgkmcnt(0)
	v_mfma_f32_16x16x32_bf16 v[2:5], v[138:141], v[14:17], v[2:5]
	s_waitcnt vmcnt(25)
	v_mfma_f32_16x16x32_bf16 v[6:9], v[134:137], v[10:13], v[6:9]
	s_waitcnt vmcnt(24)
	v_mfma_f32_16x16x32_bf16 v[154:157], v[142:145], v[14:17], v[6:9]
	s_waitcnt vmcnt(23)
	v_mfma_f32_16x16x32_bf16 v[6:9], v[146:149], v[10:13], v[18:21]
	s_waitcnt vmcnt(22)
	v_mfma_f32_16x16x32_bf16 v[146:149], v[150:153], v[14:17], v[6:9]
	s_nop 5
	v_cvt_pk_bf16_f32 v6, v154, v155
	v_cvt_pk_bf16_f32 v7, v156, v157
	v_cvt_pk_bf16_f32 v8, v146, v147
	v_cvt_pk_bf16_f32 v9, v148, v149
	ds_write2_b64 v234, v[6:7], v[8:9] offset1:4
	v_add_u32_e32 v6, 0xc0, v192
	v_ashrrev_i32_e32 v7, 31, v6
	v_lshlrev_b64 v[6:7], 12, v[6:7]
	v_lshl_add_u64 v[6:7], v[190:191], 0, v[6:7]
	v_add_co_u32_e32 v8, vcc, s30, v6
	global_store_dword v[6:7], v2, off
	s_nop 0
	v_addc_co_u32_e32 v9, vcc, 0, v7, vcc
	v_add_co_u32_e32 v2, vcc, s31, v6
	global_store_dword v[8:9], v3, off offset:-4096
	global_store_dword v[8:9], v4, off
	v_addc_co_u32_e32 v3, vcc, 0, v7, vcc
	global_store_dword v[2:3], v5, off
	v_add_co_u32_e32 v2, vcc, s51, v214
	s_waitcnt lgkmcnt(0)
	s_barrier
; DEV void gdn_scan_item(const Params& p, int item, unsigned char* lds) {
;     ...
;     LOAD_E(E0, 0); LOAD_L(L0, 0); LOAD_E(E1, 1);
;     __syncthreads();
;     for (int ch = 0; ch < 30; ch += 6) {
;         SCAN_STEP(E0, E2, L0, L1, ch);     SCAN_STEP(E1, E0, L1, L0, ch + 1); SCAN_STEP(E2, E1, L0, L1, ch + 2);
;         SCAN_STEP(E0, E2, L1, L0, ch + 3); SCAN_STEP(E1, E0, L0, L1, ch + 4); SCAN_STEP(E2, E1, L1, L0, ch + 5);
;     }
	s_nop 0
	v_addc_co_u32_e32 v3, vcc, 0, v215, vcc
	global_load_dwordx4 v[18:21], v[2:3], off
	v_add_co_u32_e32 v2, vcc, s52, v214
	s_nop 1
	v_addc_co_u32_e32 v3, vcc, 0, v215, vcc
	global_load_dwordx4 v[38:41], v[2:3], off
	v_add_co_u32_e32 v2, vcc, s51, v216
	s_nop 1
	v_addc_co_u32_e32 v3, vcc, 0, v217, vcc
	global_load_dwordx4 v[6:9], v[2:3], off
	v_add_co_u32_e32 v2, vcc, s52, v216
	s_nop 1
	v_addc_co_u32_e32 v3, vcc, 0, v217, vcc
	v_add_co_u32_e32 v10, vcc, s51, v218
	global_load_dwordx4 v[2:5], v[2:3], off
	s_nop 0
	v_addc_co_u32_e32 v11, vcc, 0, v219, vcc
	global_load_dwordx4 v[26:29], v[10:11], off
	v_add_co_u32_e32 v10, vcc, s52, v218
	s_nop 1
	v_addc_co_u32_e32 v11, vcc, 0, v219, vcc
	global_load_dwordx4 v[14:17], v[10:11], off
	v_add_co_u32_e32 v10, vcc, s51, v220
	s_nop 1
	v_addc_co_u32_e32 v11, vcc, 0, v221, vcc
	global_load_dwordx4 v[22:25], v[10:11], off
	v_add_co_u32_e32 v10, vcc, s52, v220
	s_nop 1
	v_addc_co_u32_e32 v11, vcc, 0, v221, vcc
	v_add_co_u32_e32 v122, vcc, s53, v222
	global_load_dwordx4 v[10:13], v[10:11], off
	s_nop 0
	v_addc_co_u32_e32 v123, vcc, 0, v223, vcc
	global_load_dword v193, v[122:123], off
	global_load_dword v238, v[122:123], off offset:256
	global_load_dword v239, v[122:123], off offset:512
	global_load_dword v240, v[122:123], off offset:768
	v_add_co_u32_e32 v122, vcc, s54, v224
	s_nop 1
	v_addc_co_u32_e32 v123, vcc, 0, v225, vcc
	v_add_co_u32_e32 v126, vcc, s54, v226
	global_load_dwordx4 v[122:125], v[122:123], off
	s_nop 0
	v_addc_co_u32_e32 v127, vcc, 0, v227, vcc
	v_add_co_u32_e32 v138, vcc, s55, v228
	global_load_dwordx4 v[130:133], v[126:127], off
	s_nop 0
	v_addc_co_u32_e32 v139, vcc, 0, v229, vcc
	v_add_co_u32_e32 v134, vcc, s55, v230
	global_load_dwordx4 v[126:129], v[138:139], off
	s_nop 0
	v_addc_co_u32_e32 v135, vcc, 0, v231, vcc
	global_load_dwordx4 v[134:137], v[134:135], off
	s_nop 0
	global_load_dwordx4 v[138:141], v[138:139], off offset:1024
	ds_read_b128 v[150:153], v237
	s_waitcnt lgkmcnt(0)
	v_mfma_f32_16x16x32_bf16 v[30:33], v[30:33], v[150:153], 0
	v_add_co_u32_e32 v142, vcc, s55, v232
	v_mfma_f32_16x16x32_bf16 v[34:37], v[34:37], v[150:153], 0
	ds_read_b128 v[150:153], v237 offset:64
	v_addc_co_u32_e32 v143, vcc, 0, v233, vcc
	s_waitcnt lgkmcnt(0)
	v_mfma_f32_16x16x32_bf16 v[30:33], v[42:45], v[150:153], v[30:33]
	ds_read_b128 v[42:45], v237 offset:128
	global_load_dwordx4 v[142:145], v[142:143], off
	v_mfma_f32_16x16x32_bf16 v[34:37], v[46:49], v[150:153], v[34:37]
	s_waitcnt lgkmcnt(0)
	v_mfma_f32_16x16x32_bf16 v[30:33], v[50:53], v[42:45], v[30:33]
	v_mul_f32_e64 v52, v148, s64
	v_mul_f32_e64 v53, v149, s64
	v_pk_mul_f32 v[50:51], v[146:147], s[64:65] op_sel_hi:[1,0]
	v_mfma_f32_16x16x32_bf16 v[34:37], v[54:57], v[42:45], v[34:37]
	ds_read_b128 v[42:45], v237 offset:192
	s_waitcnt lgkmcnt(0)
	v_mfma_f32_16x16x32_bf16 v[30:33], v[58:61], v[42:45], v[30:33]
	v_mfma_f32_16x16x32_bf16 v[34:37], v[62:65], v[42:45], v[34:37]
	s_nop 6
	v_sub_f32_e32 v33, v248, v33
	v_sub_f32_e32 v32, v247, v32
	v_sub_f32_e32 v31, v246, v31
	v_sub_f32_e32 v30, v245, v30
	v_cvt_pk_bf16_f32 v30, v30, v31
	v_cvt_pk_bf16_f32 v31, v32, v33
	ds_write_b64 v236, v[30:31] offset:4352
	s_waitcnt lgkmcnt(0)
	s_barrier
	ds_read_b128 v[42:45], v235 offset:4352
	ds_read_b128 v[46:49], v235 offset:4416
	s_waitcnt vmcnt(27) lgkmcnt(1)
	v_mfma_f32_16x16x32_bf16 v[30:33], v[66:69], v[42:45], v[34:37]
	s_nop 2
	v_mul_f32_e64 v36, v156, s64
	v_mul_f32_e64 v37, v157, s64
	v_pk_mul_f32 v[34:35], v[154:155], s[64:65] op_sel_hi:[1,0]
	s_waitcnt vmcnt(26) lgkmcnt(0)
	v_mfma_f32_16x16x32_bf16 v[30:33], v[74:77], v[46:49], v[30:33]
	s_waitcnt vmcnt(25)
	v_mfma_f32_16x16x32_bf16 v[34:37], v[70:73], v[42:45], v[34:37]
	s_waitcnt vmcnt(24)
	v_mfma_f32_16x16x32_bf16 v[146:149], v[78:81], v[46:49], v[34:37]
	s_waitcnt vmcnt(23)
	v_mfma_f32_16x16x32_bf16 v[34:37], v[82:85], v[42:45], v[50:53]
	s_waitcnt vmcnt(22)
	v_mfma_f32_16x16x32_bf16 v[150:153], v[86:89], v[46:49], v[34:37]
	s_nop 5
	v_cvt_pk_bf16_f32 v34, v146, v147
	v_cvt_pk_bf16_f32 v35, v148, v149
	v_cvt_pk_bf16_f32 v36, v150, v151
	v_cvt_pk_bf16_f32 v37, v152, v153
	ds_write2_b64 v234, v[34:35], v[36:37] offset1:4
	v_add_u32_e32 v34, 0x100, v192
	v_ashrrev_i32_e32 v35, 31, v34
	v_lshlrev_b64 v[34:35], 12, v[34:35]
	v_lshl_add_u64 v[34:35], v[190:191], 0, v[34:35]
	v_add_co_u32_e32 v36, vcc, s30, v34
	global_store_dword v[34:35], v30, off
	s_nop 0
	v_addc_co_u32_e32 v37, vcc, 0, v35, vcc
	v_add_co_u32_e32 v30, vcc, s31, v34
	global_store_dword v[36:37], v31, off offset:-4096
	global_store_dword v[36:37], v32, off
	v_addc_co_u32_e32 v31, vcc, 0, v35, vcc
	global_store_dword v[30:31], v33, off
	v_add_co_u32_e32 v30, vcc, s56, v214
	s_waitcnt lgkmcnt(0)
	s_barrier
; DEV void gdn_scan_item(const Params& p, int item, unsigned char* lds) {
;     ...
;     LOAD_E(E0, 0); LOAD_L(L0, 0); LOAD_E(E1, 1);
;     __syncthreads();
;     for (int ch = 0; ch < 30; ch += 6) {
;         SCAN_STEP(E0, E2, L0, L1, ch);     SCAN_STEP(E1, E0, L1, L0, ch + 1); SCAN_STEP(E2, E1, L0, L1, ch + 2);
;         SCAN_STEP(E0, E2, L1, L0, ch + 3); SCAN_STEP(E1, E0, L0, L1, ch + 4); SCAN_STEP(E2, E1, L1, L0, ch + 5);
;     }
	s_nop 0
	v_addc_co_u32_e32 v31, vcc, 0, v215, vcc
	v_add_co_u32_e32 v34, vcc, s57, v214
	global_load_dwordx4 v[30:33], v[30:31], off
	s_nop 0
	v_addc_co_u32_e32 v35, vcc, 0, v215, vcc
	v_add_co_u32_e32 v42, vcc, s56, v216
	global_load_dwordx4 v[34:37], v[34:35], off
	s_nop 0
	v_addc_co_u32_e32 v43, vcc, 0, v217, vcc
	global_load_dwordx4 v[46:49], v[42:43], off
	v_add_co_u32_e32 v42, vcc, s57, v216
	s_nop 1
	v_addc_co_u32_e32 v43, vcc, 0, v217, vcc
	global_load_dwordx4 v[50:53], v[42:43], off
	v_add_co_u32_e32 v42, vcc, s56, v218
	s_nop 1
	v_addc_co_u32_e32 v43, vcc, 0, v219, vcc
	v_add_co_u32_e32 v54, vcc, s57, v218
	global_load_dwordx4 v[42:45], v[42:43], off
	s_nop 0
	v_addc_co_u32_e32 v55, vcc, 0, v219, vcc
	v_add_co_u32_e32 v58, vcc, s56, v220
	global_load_dwordx4 v[54:57], v[54:55], off
	s_nop 0
	v_addc_co_u32_e32 v59, vcc, 0, v221, vcc
	v_add_co_u32_e32 v62, vcc, s57, v220
	global_load_dwordx4 v[58:61], v[58:59], off
	s_nop 0
	v_addc_co_u32_e32 v63, vcc, 0, v221, vcc
	v_add_co_u32_e32 v66, vcc, s58, v222
	global_load_dwordx4 v[62:65], v[62:63], off
	s_nop 0
	v_addc_co_u32_e32 v67, vcc, 0, v223, vcc
	global_load_dword v157, v[66:67], off
	global_load_dword v154, v[66:67], off offset:256
	global_load_dword v155, v[66:67], off offset:512
	global_load_dword v156, v[66:67], off offset:768
	v_add_co_u32_e32 v66, vcc, s59, v224
	s_nop 1
	v_addc_co_u32_e32 v67, vcc, 0, v225, vcc
	global_load_dwordx4 v[86:89], v[66:67], off
	v_add_co_u32_e32 v66, vcc, s59, v226
	s_nop 1
	v_addc_co_u32_e32 v67, vcc, 0, v227, vcc
	global_load_dwordx4 v[74:77], v[66:67], off
	v_add_co_u32_e32 v66, vcc, s60, v228
	s_nop 1
	v_addc_co_u32_e32 v67, vcc, 0, v229, vcc
	v_add_co_u32_e32 v68, vcc, s60, v230
	global_load_dwordx4 v[70:73], v[66:67], off
	s_nop 0
	v_addc_co_u32_e32 v69, vcc, 0, v231, vcc
	v_add_co_u32_e32 v78, vcc, s60, v232
	global_load_dwordx4 v[82:85], v[68:69], off
	s_nop 0
	global_load_dwordx4 v[66:69], v[66:67], off offset:1024
	v_addc_co_u32_e32 v79, vcc, 0, v233, vcc
	global_load_dwordx4 v[78:81], v[78:79], off
	ds_read_b128 v[214:217], v237
	s_waitcnt lgkmcnt(0)
	v_mfma_f32_16x16x32_bf16 v[90:93], v[90:93], v[214:217], 0
	v_mfma_f32_16x16x32_bf16 v[94:97], v[94:97], v[214:217], 0
	ds_read_b128 v[214:217], v237 offset:64
	s_waitcnt lgkmcnt(0)
	v_mfma_f32_16x16x32_bf16 v[90:93], v[98:101], v[214:217], v[90:93]
	ds_read_b128 v[98:101], v237 offset:128
	v_mfma_f32_16x16x32_bf16 v[94:97], v[102:105], v[214:217], v[94:97]
	s_waitcnt lgkmcnt(0)
	v_mfma_f32_16x16x32_bf16 v[90:93], v[106:109], v[98:101], v[90:93]
	v_mul_f32_e64 v108, v152, s62
	v_mul_f32_e64 v109, v153, s62
	v_pk_mul_f32 v[106:107], v[150:151], s[62:63] op_sel_hi:[1,0]
	v_mfma_f32_16x16x32_bf16 v[94:97], v[110:113], v[98:101], v[94:97]
	ds_read_b128 v[98:101], v237 offset:192
	s_waitcnt lgkmcnt(0)
	v_mfma_f32_16x16x32_bf16 v[90:93], v[114:117], v[98:101], v[90:93]
	v_mfma_f32_16x16x32_bf16 v[94:97], v[118:121], v[98:101], v[94:97]
	s_nop 6
	v_sub_f32_e32 v93, v244, v93
	v_sub_f32_e32 v92, v243, v92
	v_sub_f32_e32 v91, v242, v91
	v_sub_f32_e32 v90, v241, v90
	v_cvt_pk_bf16_f32 v90, v90, v91
	v_cvt_pk_bf16_f32 v91, v92, v93
	ds_write_b64 v236, v[90:91] offset:4352
	s_waitcnt lgkmcnt(0)
	s_barrier
	ds_read_b128 v[90:93], v235 offset:4352
	ds_read_b128 v[102:105], v235 offset:4416
	s_waitcnt vmcnt(27) lgkmcnt(1)
	v_mfma_f32_16x16x32_bf16 v[94:97], v[122:125], v[90:93], v[94:97]
	s_waitcnt vmcnt(26) lgkmcnt(0)
	v_mfma_f32_16x16x32_bf16 v[98:101], v[130:133], v[102:105], v[94:97]
	s_nop 5
	v_mul_f32_e64 v96, v148, s62
	v_mul_f32_e64 v97, v149, s62
	v_pk_mul_f32 v[94:95], v[146:147], s[62:63] op_sel_hi:[1,0]
	s_mov_b32 s62, s61
	s_waitcnt vmcnt(25)
	v_mfma_f32_16x16x32_bf16 v[94:97], v[126:129], v[90:93], v[94:97]
	s_waitcnt vmcnt(23)
	v_mfma_f32_16x16x32_bf16 v[90:93], v[138:141], v[90:93], v[106:109]
	v_mfma_f32_16x16x32_bf16 v[94:97], v[134:137], v[102:105], v[94:97]
	s_waitcnt vmcnt(22)
	v_mfma_f32_16x16x32_bf16 v[90:93], v[142:145], v[102:105], v[90:93]
	s_nop 5
	v_cvt_pk_bf16_f32 v102, v94, v95
	v_cvt_pk_bf16_f32 v103, v96, v97
	v_cvt_pk_bf16_f32 v104, v90, v91
	v_cvt_pk_bf16_f32 v105, v92, v93
	ds_write2_b64 v234, v[102:103], v[104:105] offset1:4
	v_add_u32_e32 v102, 0x140, v192
	v_ashrrev_i32_e32 v103, 31, v102
	v_lshlrev_b64 v[102:103], 12, v[102:103]
	v_lshl_add_u64 v[102:103], v[190:191], 0, v[102:103]
	v_add_co_u32_e32 v104, vcc, s30, v102
	global_store_dword v[102:103], v98, off
	s_nop 0
	v_addc_co_u32_e32 v105, vcc, 0, v103, vcc
	v_add_co_u32_e32 v98, vcc, s31, v102
	global_store_dword v[104:105], v99, off offset:-4096
	global_store_dword v[104:105], v100, off
	v_addc_co_u32_e32 v99, vcc, 0, v103, vcc
	global_store_dword v[98:99], v101, off
	s_waitcnt lgkmcnt(0)
	s_barrier
	v_add_u32_e32 v192, 0x180, v192
	s_cbranch_scc1 .LBB0_888
; DEV void gdn_scan_item(const Params& p, int item, unsigned char* lds) {
;     ...
;     SCAN_STEP(E0, E2, L0, L1, 30); SCAN_STEP(E1, E0, L1, L0, 31);
	ds_read_b128 v[98:101], v237
	ds_read_b128 v[102:105], v237 offset:64
	s_add_u32 s8, s12, 0x3e000
	s_addc_u32 s9, s13, 0
	v_lshl_add_u64 v[106:107], s[8:9], 0, v[180:181]
	s_waitcnt lgkmcnt(1)
	v_mfma_f32_16x16x32_bf16 v[18:21], v[18:21], v[98:101], 0
	v_or_b32_e32 v108, 0x400, v184
	v_add3_u32 v1, v1, s24, v179
	s_movk_i32 s13, 0x2000
	v_mfma_f32_16x16x32_bf16 v[38:41], v[38:41], v[98:101], 0
	v_lshl_add_u64 v[98:99], s[8:9], 0, v[182:183]
	s_add_u32 s8, s10, 0x7c000
	s_addc_u32 s9, s11, 0
	s_waitcnt lgkmcnt(0)
	v_mfma_f32_16x16x32_bf16 v[6:9], v[6:9], v[102:105], v[18:21]
	v_lshl_add_u64 v[100:101], s[8:9], 0, v[184:185]
	v_lshl_add_u64 v[110:111], s[8:9], 0, v[188:189]
	s_lshl_b32 s10, s23, 2
	ds_read_b128 v[18:21], v237 offset:128
	v_mfma_f32_16x16x32_bf16 v[2:5], v[2:5], v[102:105], v[38:41]
	s_nop 2
	global_load_dwordx4 v[38:41], v[98:99], off
	s_nop 0
	global_load_dwordx4 v[98:101], v[100:101], off
	ds_read_b128 v[102:105], v237 offset:192
	s_movk_i32 s16, 0x3000
	s_waitcnt lgkmcnt(1)
	v_mfma_f32_16x16x32_bf16 v[6:9], v[26:29], v[18:21], v[6:9]
	global_load_dwordx4 v[26:29], v[106:107], off
	s_nop 0
	global_load_dwordx4 v[106:109], v108, s[8:9]
	v_readlane_b32 s12, v177, 31
	s_lshl_b64 s[4:5], s[4:5], 7
	v_mfma_f32_16x16x32_bf16 v[2:5], v[14:17], v[18:21], v[2:5]
	v_lshl_add_u64 v[18:19], s[8:9], 0, v[186:187]
	global_load_dwordx4 v[14:17], v[110:111], off
	s_nop 0
	global_load_dwordx4 v[18:21], v[18:19], off
	v_readlane_b32 s8, v177, 30
	s_waitcnt lgkmcnt(0)
	v_mfma_f32_16x16x32_bf16 v[6:9], v[22:25], v[102:105], v[6:9]
	v_ashrrev_i32_e32 v177, 31, v176
	v_pk_mul_f32 v[24:25], v[96:97], s[8:9] op_sel_hi:[1,0]
	v_pk_mul_f32 v[22:23], v[94:95], s[8:9] op_sel_hi:[1,0]
	v_mfma_f32_16x16x32_bf16 v[2:5], v[10:13], v[102:105], v[2:5]
	s_nop 3
	v_sub_f32_e32 v9, v240, v9
	v_sub_f32_e32 v8, v239, v8
	v_sub_f32_e32 v7, v238, v7
	v_sub_f32_e32 v6, v193, v6
	v_cvt_pk_bf16_f32 v6, v6, v7
	v_cvt_pk_bf16_f32 v7, v8, v9
	ds_write_b64 v236, v[6:7] offset:4352
	s_waitcnt lgkmcnt(0)
	s_barrier
	ds_read_b128 v[6:9], v235 offset:4352
	ds_read_b128 v[10:13], v235 offset:4416
	s_waitcnt vmcnt(13) lgkmcnt(1)
	v_mfma_f32_16x16x32_bf16 v[22:25], v[70:73], v[6:9], v[22:25]
	v_mul_f32_e64 v72, v92, s8
	v_mul_f32_e64 v73, v93, s8
	v_pk_mul_f32 v[70:71], v[90:91], s[8:9] op_sel_hi:[1,0]
	s_mov_b32 s9, 0
	v_mfma_f32_16x16x32_bf16 v[2:5], v[86:89], v[6:9], v[2:5]
	s_lshl_b32 s8, s22, 2
	s_mov_b32 s11, s9
	s_waitcnt vmcnt(11)
	v_mfma_f32_16x16x32_bf16 v[6:9], v[66:69], v[6:9], v[70:73]
	s_waitcnt lgkmcnt(0)
	v_mfma_f32_16x16x32_bf16 v[22:25], v[82:85], v[10:13], v[22:25]
	s_waitcnt vmcnt(10)
	v_mfma_f32_16x16x32_bf16 v[6:9], v[78:81], v[10:13], v[6:9]
	v_mfma_f32_16x16x32_bf16 v[2:5], v[74:77], v[10:13], v[2:5]
	v_add_u32_e32 v10, 0x780, v1
	v_ashrrev_i32_e32 v11, 31, v10
	v_lshlrev_b64 v[10:11], 12, v[10:11]
	v_lshl_add_u64 v[10:11], s[6:7], 0, v[10:11]
	s_nop 0
	v_cvt_pk_bf16_f32 v66, v22, v23
	v_cvt_pk_bf16_f32 v67, v24, v25
	v_cvt_pk_bf16_f32 v68, v6, v7
	v_cvt_pk_bf16_f32 v69, v8, v9
	v_lshl_add_u64 v[10:11], v[10:11], 0, s[8:9]
	ds_write2_b64 v234, v[66:67], v[68:69] offset1:4
	v_lshl_add_u64 v[10:11], v[10:11], 0, s[10:11]
	v_lshlrev_b32_e32 v66, 2, v178
	v_mov_b32_e32 v67, 0
	v_lshl_add_u64 v[10:11], v[10:11], 0, v[66:67]
	v_add_co_u32_e32 v12, vcc, s13, v10
	global_store_dword v[10:11], v2, off
	s_nop 0
	v_addc_co_u32_e32 v13, vcc, 0, v11, vcc
	v_add_co_u32_e32 v2, vcc, s16, v10
	global_store_dword v[12:13], v3, off offset:-4096
	global_store_dword v[12:13], v4, off
	v_addc_co_u32_e32 v3, vcc, 0, v11, vcc
	global_store_dword v[2:3], v5, off
	s_waitcnt lgkmcnt(0)
	s_barrier
; DEV void xcd_barrier(const XcdBarrier& b) {
;     asm volatile("s_waitcnt vmcnt(0)" ::: "memory");
;     __syncthreads();
;     if (threadIdx.x == 0) {
;         unsigned* bar = b.bar;
;         __builtin_amdgcn_s_waitcnt(0);
;         unsigned nloc = b.st[0], nx = b.st[1];
;         if (nloc == 0u) { xcd_barrier_complete(bar, b.x, nloc, nx); b.st[0] = nloc; b.st[1] = nx; }
; DEV void gdn_scan_item(const Params& p, int item, unsigned char* lds) {
;     ...
;     LOAD_E(E0, 0); LOAD_L(L0, 0); LOAD_E(E1, 1);
;     __syncthreads();
;     for (int ch = 0; ch < 30; ch += 6) {
;         SCAN_STEP(E0, E2, L0, L1, ch);     SCAN_STEP(E1, E0, L1, L0, ch + 1); SCAN_STEP(E2, E1, L0, L1, ch + 2);
;         SCAN_STEP(E0, E2, L1, L0, ch + 3); SCAN_STEP(E1, E0, L0, L1, ch + 4); SCAN_STEP(E2, E1, L1, L0, ch + 5);
;     }
;     SCAN_STEP(E0, E2, L0, L1, 30); SCAN_STEP(E1, E0, L1, L0, 31);
;     ...
;     {
;         float* dp = p.out + O_DP + ((size_t)bh * 128 + w * 32 + fq * 4) * 128 + s * 16 + fr;
; #pragma unroll
;         for (int e = 0; e < 4; ++e) { dp[e * 128] = S0[e]; dp[(16 + e) * 128] = S1[e]; }
;     }
;     __syncthreads();
	ds_read_b128 v[2:5], v237
	ds_read_b128 v[10:13], v237 offset:64
	s_waitcnt lgkmcnt(1)
	v_mfma_f32_16x16x32_bf16 v[30:33], v[30:33], v[2:5], 0
	v_mul_f32_e64 v24, v24, s12
	v_mul_f32_e64 v25, v25, s12
	v_pk_mul_f32 v[22:23], v[22:23], s[12:13] op_sel_hi:[1,0]
	v_pk_mul_f32 v[8:9], v[8:9], s[12:13] op_sel_hi:[1,0]
	v_mfma_f32_16x16x32_bf16 v[2:5], v[34:37], v[2:5], 0
	v_mul_f32_e64 v6, v6, s12
	v_mul_f32_e64 v7, v7, s12
	s_waitcnt lgkmcnt(0)
	v_mfma_f32_16x16x32_bf16 v[30:33], v[46:49], v[10:13], v[30:33]
	v_mfma_f32_16x16x32_bf16 v[2:5], v[50:53], v[10:13], v[2:5]
	ds_read_b128 v[10:13], v237 offset:128
	ds_read_b128 v[34:37], v237 offset:192
	s_waitcnt lgkmcnt(1)
	v_mfma_f32_16x16x32_bf16 v[30:33], v[42:45], v[10:13], v[30:33]
	v_mfma_f32_16x16x32_bf16 v[2:5], v[54:57], v[10:13], v[2:5]
	s_waitcnt lgkmcnt(0)
	v_mfma_f32_16x16x32_bf16 v[10:13], v[58:61], v[34:37], v[30:33]
	v_mfma_f32_16x16x32_bf16 v[2:5], v[62:65], v[34:37], v[2:5]
	s_nop 6
	v_sub_f32_e32 v13, v156, v13
	v_sub_f32_e32 v12, v155, v12
	v_sub_f32_e32 v11, v154, v11
	v_sub_f32_e32 v10, v157, v10
	v_cvt_pk_bf16_f32 v10, v10, v11
	v_cvt_pk_bf16_f32 v11, v12, v13
	ds_write_b64 v236, v[10:11] offset:4352
	s_waitcnt lgkmcnt(0)
	s_barrier
	ds_read_b128 v[10:13], v235 offset:4352
	ds_read_b128 v[30:33], v235 offset:4416
	s_waitcnt vmcnt(8) lgkmcnt(1)
	v_mfma_f32_16x16x32_bf16 v[22:25], v[98:101], v[10:13], v[22:25]
	s_waitcnt vmcnt(6)
	v_mfma_f32_16x16x32_bf16 v[6:9], v[106:109], v[10:13], v[6:9]
	s_waitcnt vmcnt(5) lgkmcnt(0)
	v_mfma_f32_16x16x32_bf16 v[14:17], v[14:17], v[30:33], v[22:25]
	s_waitcnt vmcnt(4)
	v_mfma_f32_16x16x32_bf16 v[6:9], v[18:21], v[30:33], v[6:9]
	v_mfma_f32_16x16x32_bf16 v[2:5], v[26:29], v[10:13], v[2:5]
	s_nop 4
	v_cvt_pk_bf16_f32 v10, v14, v15
	v_cvt_pk_bf16_f32 v11, v16, v17
	v_cvt_pk_bf16_f32 v12, v6, v7
	v_cvt_pk_bf16_f32 v13, v8, v9
	ds_write2_b64 v234, v[10:11], v[12:13] offset1:4
	v_add_u32_e32 v10, 0x7c0, v1
	v_ashrrev_i32_e32 v11, 31, v10
	v_lshlrev_b64 v[10:11], 12, v[10:11]
	v_lshl_add_u64 v[10:11], s[6:7], 0, v[10:11]
	v_lshl_add_u64 v[10:11], v[10:11], 0, s[8:9]
	v_mfma_f32_16x16x32_bf16 v[2:5], v[38:41], v[30:33], v[2:5]
	v_lshl_add_u64 v[10:11], v[10:11], 0, s[10:11]
	v_lshl_add_u64 v[10:11], v[10:11], 0, v[66:67]
	v_add_co_u32_e32 v12, vcc, s13, v10
	s_nop 1
	v_addc_co_u32_e32 v13, vcc, 0, v11, vcc
	s_nop 1
	global_store_dword v[10:11], v2, off
	v_add_co_u32_e32 v2, vcc, s16, v10
	global_store_dword v[12:13], v3, off offset:-4096
	global_store_dword v[12:13], v4, off
	v_addc_co_u32_e32 v3, vcc, 0, v11, vcc
	global_store_dword v[2:3], v5, off
	s_waitcnt lgkmcnt(0)
	s_barrier
	s_load_dwordx2 s[6:7], s[0:1], 0xc0
	v_lshl_add_u64 v[2:3], s[4:5], 0, v[176:177]
	v_or_b32_e32 v2, v2, v179
	v_lshlrev_b64 v[2:3], 9, v[2:3]
	s_mov_b64 s[4:5], 0x5400000
	s_waitcnt lgkmcnt(0)
	v_lshl_add_u64 v[2:3], s[6:7], 0, v[2:3]
	v_lshl_add_u64 v[2:3], v[2:3], 0, s[10:11]
	v_lshl_add_u64 v[2:3], v[2:3], 0, v[66:67]
	v_lshl_add_u64 v[4:5], v[2:3], 0, s[4:5]
	s_mov_b32 s4, 0x5400000
	v_add_co_u32_e32 v10, vcc, s4, v2
	s_nop 1
	v_addc_co_u32_e32 v11, vcc, 0, v3, vcc
	v_add_co_u32_e32 v2, vcc, 0x5402000, v2
	global_store_dword v[10:11], v14, off
	s_nop 0
	v_addc_co_u32_e32 v3, vcc, 0, v3, vcc
	global_store_dword v[2:3], v6, off
	global_store_dword v[4:5], v15, off offset:512
	global_store_dword v[2:3], v7, off offset:512
	global_store_dword v[4:5], v16, off offset:1024
	global_store_dword v[2:3], v8, off offset:1024
	global_store_dword v[4:5], v17, off offset:1536
	global_store_dword v[2:3], v9, off offset:1536
	s_barrier
.LBB0_890:
	s_waitcnt vmcnt(0)
	s_barrier
	s_and_saveexec_b64 s[4:5], s[94:95]
	s_cbranch_execz .LBB0_942
	v_mov_b32_e32 v1, 0x20000
	s_waitcnt vmcnt(0) expcnt(0) lgkmcnt(0)
	ds_read_b32 v3, v1
	v_mov_b32_e32 v1, 0x20004
	ds_read_b32 v1, v1
	s_waitcnt lgkmcnt(1)
	v_cmp_ne_u32_e32 vcc, 0, v3
	s_cbranch_vccnz .LBB0_906
	s_add_u32 s6, s28, 0x1000
	s_addc_u32 s7, s29, 0
	s_add_u32 s8, s28, 0x1100
	s_addc_u32 s9, s29, 0
	s_add_u32 s10, s28, 0x1200
	s_addc_u32 s11, s29, 0
	s_add_u32 s12, s28, 0x1300
	s_addc_u32 s13, s29, 0
	s_mov_b32 s22, 1
	v_mov_b32_e32 v17, 0
	s_branch .LBB0_894
